# v20 + attention O-store epilogue: lane^1 exchange by DPP quad_perm instead of ds_bpermute
# speedup vs baseline: 1.0882x; 1.0019x over previous
.LBB0_482:
	v_cndmask_b32_e64 v149, v149, v213, s[14:15]
	v_mul_f32_e32 v149, 0xbe0293ee, v149
	v_fmamk_f32 v82, v82, 0x3e0293ee, v149
	v_fmamk_f32 v83, v83, 0x3e0293ee, v149
	v_fmamk_f32 v150, v84, 0x3e0293ee, v149
	v_exp_f32_e32 v84, v82
	v_fmamk_f32 v151, v86, 0x3e0293ee, v149
	v_exp_f32_e32 v86, v83
	v_fmamk_f32 v85, v85, 0x3e0293ee, v149
	v_exp_f32_e32 v82, v150
	v_fmamk_f32 v66, v66, 0x3e0293ee, v149
	v_exp_f32_e32 v85, v85
	v_fmamk_f32 v152, v87, 0x3e0293ee, v149
	v_fmamk_f32 v161, v96, 0x3e0293ee, v149
	v_fmamk_f32 v96, v77, 0x3e0293ee, v149
	v_exp_f32_e32 v77, v151
	v_exp_f32_e32 v150, v66
	v_add_f32_e32 v66, 0, v84
	v_fmamk_f32 v153, v88, 0x3e0293ee, v149
	v_exp_f32_e32 v83, v152
	v_add_f32_e32 v66, v86, v66
	v_fmamk_f32 v154, v89, 0x3e0293ee, v149
	v_fmamk_f32 v160, v95, 0x3e0293ee, v149
	v_fmamk_f32 v95, v76, 0x3e0293ee, v149
	v_exp_f32_e32 v76, v153
	v_add_f32_e32 v66, v82, v66
	v_fmamk_f32 v155, v90, 0x3e0293ee, v149
	v_fmamk_f32 v166, v97, 0x3e0293ee, v149
	v_fmamk_f32 v97, v78, 0x3e0293ee, v149
	v_exp_f32_e32 v78, v154
	v_add_f32_e32 v66, v85, v66
	v_fmamk_f32 v156, v91, 0x3e0293ee, v149
	v_fmamk_f32 v157, v92, 0x3e0293ee, v149
	v_fmamk_f32 v92, v73, 0x3e0293ee, v149
	v_exp_f32_e32 v73, v155
	v_add_f32_e32 v66, v77, v66
	v_fmamk_f32 v159, v94, 0x3e0293ee, v149
	v_fmamk_f32 v94, v75, 0x3e0293ee, v149
	v_exp_f32_e32 v75, v156
	v_add_f32_e32 v66, v83, v66
	v_fmamk_f32 v158, v93, 0x3e0293ee, v149
	v_fmamk_f32 v90, v71, 0x3e0293ee, v149
	v_exp_f32_e32 v71, v157
	v_add_f32_e32 v66, v76, v66
	v_fmamk_f32 v93, v74, 0x3e0293ee, v149
	v_exp_f32_e32 v74, v158
	v_add_f32_e32 v66, v78, v66
	v_fmamk_f32 v88, v69, 0x3e0293ee, v149
	v_exp_f32_e32 v69, v159
	v_add_f32_e32 v66, v73, v66
	v_fmamk_f32 v91, v72, 0x3e0293ee, v149
	v_exp_f32_e32 v72, v160
	v_add_f32_e32 v66, v75, v66
	v_fmamk_f32 v87, v68, 0x3e0293ee, v149
	v_exp_f32_e32 v68, v161
	v_add_f32_e32 v66, v71, v66
	v_fmamk_f32 v89, v70, 0x3e0293ee, v149
	v_exp_f32_e32 v70, v166
	v_add_f32_e32 v66, v74, v66
	v_fmamk_f32 v67, v67, 0x3e0293ee, v149
	v_add_f32_e32 v66, v69, v66
	v_exp_f32_e32 v151, v67
	v_add_f32_e32 v66, v72, v66
	v_exp_f32_e32 v87, v87
	v_add_f32_e32 v66, v68, v66
	v_exp_f32_e32 v88, v88
	v_add_f32_e32 v66, v70, v66
	v_exp_f32_e32 v89, v89
	v_add_f32_e32 v66, v150, v66
	v_exp_f32_e32 v90, v90
	v_add_f32_e32 v66, v151, v66
	v_exp_f32_e32 v91, v91
	v_add_f32_e32 v66, v87, v66
	v_exp_f32_e32 v92, v92
	v_add_f32_e32 v66, v88, v66
	v_exp_f32_e32 v93, v93
	v_add_f32_e32 v66, v89, v66
	v_exp_f32_e32 v94, v94
	v_add_f32_e32 v66, v90, v66
	v_exp_f32_e32 v95, v95
	v_add_f32_e32 v66, v91, v66
	v_exp_f32_e32 v96, v96
	v_add_f32_e32 v66, v92, v66
	v_fmamk_f32 v79, v79, 0x3e0293ee, v149
	v_exp_f32_e32 v97, v97
	v_add_f32_e32 v66, v93, v66
	v_fmamk_f32 v80, v80, 0x3e0293ee, v149
	v_exp_f32_e32 v152, v79
	v_add_f32_e32 v66, v94, v66
	v_fmac_f32_e32 v149, 0x3e0293ee, v81
	v_exp_f32_e32 v153, v80
	v_add_f32_e32 v66, v95, v66
	v_exp_f32_e32 v149, v149
	v_add_f32_e32 v66, v96, v66
	v_add_f32_e32 v66, v97, v66
	v_add_f32_e32 v66, v152, v66
	v_add_f32_e32 v66, v153, v66
	v_add_f32_e32 v66, v149, v66
	v_mov_b32_e32 v67, v66
	s_nop 1
	v_permlane32_swap_b32_e32 v66, v67
	v_cvt_pk_bf16_f32 v80, v84, v86
	v_cvt_pk_bf16_f32 v81, v82, v85
	v_cvt_pk_bf16_f32 v82, v77, v83
	v_cvt_pk_bf16_f32 v83, v76, v78
	v_cvt_pk_bf16_f32 v76, v73, v75
	v_cvt_pk_bf16_f32 v77, v71, v74
	v_cvt_pk_bf16_f32 v78, v69, v72
	v_cvt_pk_bf16_f32 v79, v68, v70
	v_cvt_pk_bf16_f32 v68, v150, v151
	v_cvt_pk_bf16_f32 v69, v87, v88
	v_cvt_pk_bf16_f32 v70, v89, v90
	v_cvt_pk_bf16_f32 v71, v91, v92
	v_cvt_pk_bf16_f32 v72, v93, v94
	v_cvt_pk_bf16_f32 v73, v95, v96
	v_cvt_pk_bf16_f32 v74, v97, v152
	v_cvt_pk_bf16_f32 v75, v153, v149
	s_nop 0
	v_permlane32_swap_b32_e32 v80, v82
	v_permlane32_swap_b32_e32 v81, v83
	v_permlane32_swap_b32_e32 v76, v78
	v_permlane32_swap_b32_e32 v77, v79
	v_permlane32_swap_b32_e32 v68, v70
	v_permlane32_swap_b32_e32 v69, v71
	v_permlane32_swap_b32_e32 v72, v74
	v_permlane32_swap_b32_e32 v73, v75
	ds_read_b64_tr_b16 v[84:85], v203 offset:0x4000
	ds_read_b64_tr_b16 v[86:87], v203 offset:0x4800
	ds_read_b64_tr_b16 v[88:89], v203 offset:0x5000
	ds_read_b64_tr_b16 v[90:91], v203 offset:0x5800
	ds_read_b64_tr_b16 v[92:93], v203 offset:0x6000
	ds_read_b64_tr_b16 v[94:95], v203 offset:0x6800
	ds_read_b64_tr_b16 v[150:151], v203 offset:0x7000
	ds_read_b64_tr_b16 v[152:153], v203 offset:0x7800
	s_waitcnt lgkmcnt(0)
	s_nop 0
	v_mfma_f32_32x32x16_bf16 v[34:49], v[80:83], v[84:87], v[34:49]
	ds_read_b64_tr_b16 v[84:85], v203 offset:0x4200
	ds_read_b64_tr_b16 v[86:87], v203 offset:0x4a00
	v_mfma_f32_32x32x16_bf16 v[34:49], v[76:79], v[88:91], v[34:49]
	ds_read_b64_tr_b16 v[88:89], v203 offset:0x5200
	ds_read_b64_tr_b16 v[90:91], v203 offset:0x5a00
	v_mfma_f32_32x32x16_bf16 v[34:49], v[68:71], v[92:95], v[34:49]
	ds_read_b64_tr_b16 v[92:93], v203 offset:0x6200
	ds_read_b64_tr_b16 v[94:95], v203 offset:0x6a00
	ds_read_b64_tr_b16 v[154:155], v203 offset:0x7200
	ds_read_b64_tr_b16 v[156:157], v203 offset:0x7a00
	s_waitcnt lgkmcnt(0)
	v_mfma_f32_32x32x16_bf16 v[34:49], v[72:75], v[150:153], v[34:49]
	v_mfma_f32_32x32x16_bf16 v[50:65], v[80:83], v[84:87], v[50:65]
	ds_read_b64_tr_b16 v[84:85], v203 offset:0x4400
	ds_read_b64_tr_b16 v[86:87], v203 offset:0x4c00
	v_mfma_f32_32x32x16_bf16 v[50:65], v[76:79], v[88:91], v[50:65]
	ds_read_b64_tr_b16 v[88:89], v203 offset:0x5400
	ds_read_b64_tr_b16 v[90:91], v203 offset:0x5c00
	v_mfma_f32_32x32x16_bf16 v[50:65], v[68:71], v[92:95], v[50:65]
	ds_read_b64_tr_b16 v[92:93], v203 offset:0x6400
	ds_read_b64_tr_b16 v[94:95], v203 offset:0x6c00
	ds_read_b64_tr_b16 v[150:151], v203 offset:0x7400
	ds_read_b64_tr_b16 v[152:153], v203 offset:0x7c00
	s_waitcnt lgkmcnt(0)
	v_mfma_f32_32x32x16_bf16 v[50:65], v[72:75], v[154:157], v[50:65]
	v_mfma_f32_32x32x16_bf16 v[18:33], v[80:83], v[84:87], v[18:33]
	ds_read_b64_tr_b16 v[84:85], v203 offset:0x4600
	ds_read_b64_tr_b16 v[86:87], v203 offset:0x4e00
	v_mfma_f32_32x32x16_bf16 v[18:33], v[76:79], v[88:91], v[18:33]
	ds_read_b64_tr_b16 v[88:89], v203 offset:0x5600
	ds_read_b64_tr_b16 v[90:91], v203 offset:0x5e00
	v_mfma_f32_32x32x16_bf16 v[18:33], v[68:71], v[92:95], v[18:33]
	ds_read_b64_tr_b16 v[92:93], v203 offset:0x6600
	ds_read_b64_tr_b16 v[94:95], v203 offset:0x6e00
	ds_read_b64_tr_b16 v[154:155], v203 offset:0x7600
	ds_read_b64_tr_b16 v[156:157], v203 offset:0x7e00
	s_waitcnt lgkmcnt(0)
	v_mfma_f32_32x32x16_bf16 v[18:33], v[72:75], v[150:153], v[18:33]
	v_mfma_f32_32x32x16_bf16 v[2:17], v[80:83], v[84:87], v[2:17]
	v_mfma_f32_32x32x16_bf16 v[2:17], v[76:79], v[88:91], v[2:17]
	v_mfma_f32_32x32x16_bf16 v[2:17], v[68:71], v[92:95], v[2:17]
	v_mfma_f32_32x32x16_bf16 v[2:17], v[72:75], v[154:157], v[2:17]
	s_waitcnt vmcnt(8)
	s_waitcnt vmcnt(9)
	ds_write_b128 v206, v[138:141] offset:32768
	s_waitcnt vmcnt(8)
	ds_write_b128 v206, v[142:145] offset:40960
	s_and_saveexec_b64 s[14:15], s[12:13]
	v_add_f32_e32 v68, v146, v147
	v_fmac_f32_e32 v68, v207, v182
	v_add_f32_e32 v66, v66, v67
	v_fmac_f32_e32 v66, v68, v148
	ds_write_b32 v205, v66
	s_or_b64 exec, exec, s[14:15]
	s_waitcnt lgkmcnt(0)
	ds_read_b128 v[78:81], v204
	s_ashr_i32 s21, s20, 31
	ds_read_b128 v[74:77], v204 offset:32
	ds_read_b128 v[70:73], v204 offset:64
	ds_read_b128 v[66:69], v204 offset:96
	s_lshl_b64 s[12:13], s[20:21], 13
	s_add_u32 s14, s26, s12
	s_waitcnt lgkmcnt(3)
	v_rcp_f32_e32 v78, v78
	s_addc_u32 s15, s27, s13
	v_and_b32_e32 v82, 1, v202
	v_lshlrev_b32_e32 v166, 1, v201
	v_mul_f32_e32 v34, v34, v78
	s_nop 1
	v_mov_b32_dpp v84, v34 quad_perm:[1,0,3,2] row_mask:0xf bank_mask:0xf
	v_cmp_eq_u32_e64 s[12:13], 0, v82
	v_lshl_add_u64 v[82:83], s[14:15], 0, v[166:167]
	v_lshlrev_b32_e32 v166, 15, v200
	v_lshl_add_u64 v[82:83], v[82:83], 0, v[166:167]
	s_and_saveexec_b64 s[14:15], s[12:13]
	s_cbranch_execz .LBB0_486
	s_waitcnt lgkmcnt(0)
	v_cvt_pk_bf16_f32 v34, v34, v84
	global_store_dword v[82:83], v34, off
.LBB0_486:
	s_or_b64 exec, exec, s[14:15]
	v_mul_f32_e32 v34, v50, v78
	s_nop 1
	v_mov_b32_dpp v50, v34 quad_perm:[1,0,3,2] row_mask:0xf bank_mask:0xf
	s_and_saveexec_b64 s[14:15], s[12:13]
	s_cbranch_execz .LBB0_488
	s_waitcnt lgkmcnt(0)
	v_cvt_pk_bf16_f32 v34, v34, v50
	global_store_dword v[82:83], v34, off offset:64
.LBB0_488:
	s_or_b64 exec, exec, s[14:15]
	v_mul_f32_e32 v18, v18, v78
	s_nop 1
	v_mov_b32_dpp v34, v18 quad_perm:[1,0,3,2] row_mask:0xf bank_mask:0xf
	s_and_saveexec_b64 s[14:15], s[12:13]
	s_cbranch_execz .LBB0_490
	s_waitcnt lgkmcnt(0)
	v_cvt_pk_bf16_f32 v18, v18, v34
	global_store_dword v[82:83], v18, off offset:128
.LBB0_490:
	s_or_b64 exec, exec, s[14:15]
	v_mul_f32_e32 v2, v2, v78
	s_nop 1
	v_mov_b32_dpp v18, v2 quad_perm:[1,0,3,2] row_mask:0xf bank_mask:0xf
	s_and_saveexec_b64 s[14:15], s[12:13]
	s_cbranch_execz .LBB0_492
	s_waitcnt lgkmcnt(0)
	v_cvt_pk_bf16_f32 v2, v2, v18
	global_store_dword v[82:83], v2, off offset:192
.LBB0_492:
	s_or_b64 exec, exec, s[14:15]
	v_rcp_f32_e32 v2, v79
	s_waitcnt lgkmcnt(0)
	v_mul_f32_e32 v18, v35, v2
	s_nop 1
	v_mov_b32_dpp v34, v18 quad_perm:[1,0,3,2] row_mask:0xf bank_mask:0xf
	s_and_saveexec_b64 s[14:15], s[12:13]
	s_cbranch_execz .LBB0_494
	s_waitcnt lgkmcnt(0)
	v_cvt_pk_bf16_f32 v18, v18, v34
	v_add_co_u32_e32 v34, vcc, 0x2000, v82
	s_nop 1
	v_addc_co_u32_e32 v35, vcc, 0, v83, vcc
	global_store_dword v[34:35], v18, off
.LBB0_494:
	s_or_b64 exec, exec, s[14:15]
	v_mul_f32_e32 v18, v51, v2
	s_waitcnt lgkmcnt(0)
	s_nop 1
	v_mov_b32_dpp v34, v18 quad_perm:[1,0,3,2] row_mask:0xf bank_mask:0xf
	s_and_saveexec_b64 s[14:15], s[12:13]
	s_cbranch_execz .LBB0_496
	s_waitcnt lgkmcnt(0)
	v_cvt_pk_bf16_f32 v18, v18, v34
	v_add_co_u32_e32 v34, vcc, 0x2000, v82
	s_nop 1
	v_addc_co_u32_e32 v35, vcc, 0, v83, vcc
	global_store_dword v[34:35], v18, off offset:64
.LBB0_496:
	s_or_b64 exec, exec, s[14:15]
	v_mul_f32_e32 v18, v19, v2
	s_nop 1
	v_mov_b32_dpp v19, v18 quad_perm:[1,0,3,2] row_mask:0xf bank_mask:0xf
	s_and_saveexec_b64 s[14:15], s[12:13]
	s_cbranch_execz .LBB0_498
	s_waitcnt lgkmcnt(0)
	v_cvt_pk_bf16_f32 v34, v18, v19
	v_add_co_u32_e32 v18, vcc, 0x2000, v82
	s_nop 1
	v_addc_co_u32_e32 v19, vcc, 0, v83, vcc
	global_store_dword v[18:19], v34, off offset:128
.LBB0_498:
	s_or_b64 exec, exec, s[14:15]
	v_mul_f32_e32 v2, v3, v2
	s_nop 1
	v_mov_b32_dpp v3, v2 quad_perm:[1,0,3,2] row_mask:0xf bank_mask:0xf
	s_and_saveexec_b64 s[14:15], s[12:13]
	s_cbranch_execz .LBB0_500
	s_waitcnt lgkmcnt(0)
	v_cvt_pk_bf16_f32 v18, v2, v3
	v_add_co_u32_e32 v2, vcc, 0x2000, v82
	s_nop 1
	v_addc_co_u32_e32 v3, vcc, 0, v83, vcc
	global_store_dword v[2:3], v18, off offset:192
.LBB0_500:
	s_or_b64 exec, exec, s[14:15]
	v_rcp_f32_e32 v2, v80
	s_waitcnt lgkmcnt(0)
	v_mul_f32_e32 v3, v36, v2
	s_nop 1
	v_mov_b32_dpp v18, v3 quad_perm:[1,0,3,2] row_mask:0xf bank_mask:0xf
	s_and_saveexec_b64 s[14:15], s[12:13]
	s_cbranch_execz .LBB0_502
	s_waitcnt lgkmcnt(0)
	v_cvt_pk_bf16_f32 v3, v3, v18
	v_add_co_u32_e32 v18, vcc, 0x4000, v82
	s_nop 1
	v_addc_co_u32_e32 v19, vcc, 0, v83, vcc
	global_store_dword v[18:19], v3, off
.LBB0_502:
	s_or_b64 exec, exec, s[14:15]
	v_mul_f32_e32 v3, v52, v2
	s_waitcnt lgkmcnt(0)
	s_nop 1
	v_mov_b32_dpp v18, v3 quad_perm:[1,0,3,2] row_mask:0xf bank_mask:0xf
	s_and_saveexec_b64 s[14:15], s[12:13]
	s_cbranch_execz .LBB0_504
	s_waitcnt lgkmcnt(0)
	v_cvt_pk_bf16_f32 v3, v3, v18
	v_add_co_u32_e32 v18, vcc, 0x4000, v82
	s_nop 1
	v_addc_co_u32_e32 v19, vcc, 0, v83, vcc
	global_store_dword v[18:19], v3, off offset:64
.LBB0_504:
	s_or_b64 exec, exec, s[14:15]
	v_mul_f32_e32 v3, v20, v2
	s_waitcnt lgkmcnt(0)
	s_nop 1
	v_mov_b32_dpp v18, v3 quad_perm:[1,0,3,2] row_mask:0xf bank_mask:0xf
	s_and_saveexec_b64 s[14:15], s[12:13]
	s_cbranch_execz .LBB0_506
	s_waitcnt lgkmcnt(0)
	v_cvt_pk_bf16_f32 v3, v3, v18
	v_add_co_u32_e32 v18, vcc, 0x4000, v82
	s_nop 1
	v_addc_co_u32_e32 v19, vcc, 0, v83, vcc
	global_store_dword v[18:19], v3, off offset:128
.LBB0_506:
	s_or_b64 exec, exec, s[14:15]
	v_mul_f32_e32 v2, v4, v2
	s_nop 1
	v_mov_b32_dpp v3, v2 quad_perm:[1,0,3,2] row_mask:0xf bank_mask:0xf
	s_and_saveexec_b64 s[14:15], s[12:13]
	s_cbranch_execz .LBB0_508
	s_waitcnt lgkmcnt(0)
	v_cvt_pk_bf16_f32 v4, v2, v3
	v_add_co_u32_e32 v2, vcc, 0x4000, v82
	s_nop 1
	v_addc_co_u32_e32 v3, vcc, 0, v83, vcc
	global_store_dword v[2:3], v4, off offset:192
.LBB0_508:
	s_or_b64 exec, exec, s[14:15]
	v_rcp_f32_e32 v2, v81
	s_waitcnt lgkmcnt(0)
	v_mul_f32_e32 v3, v37, v2
	s_nop 1
	v_mov_b32_dpp v4, v3 quad_perm:[1,0,3,2] row_mask:0xf bank_mask:0xf
	s_and_saveexec_b64 s[14:15], s[12:13]
	s_cbranch_execz .LBB0_510
	v_add_co_u32_e32 v18, vcc, 0x6000, v82
	s_waitcnt lgkmcnt(0)
	v_cvt_pk_bf16_f32 v3, v3, v4
	s_nop 0
	v_addc_co_u32_e32 v19, vcc, 0, v83, vcc
	global_store_dword v[18:19], v3, off
.LBB0_510:
	s_or_b64 exec, exec, s[14:15]
	v_mul_f32_e32 v3, v53, v2
	s_waitcnt lgkmcnt(0)
	s_nop 1
	v_mov_b32_dpp v4, v3 quad_perm:[1,0,3,2] row_mask:0xf bank_mask:0xf
	s_and_saveexec_b64 s[14:15], s[12:13]
	s_cbranch_execz .LBB0_512
	v_add_co_u32_e32 v18, vcc, 0x6000, v82
	s_waitcnt lgkmcnt(0)
	v_cvt_pk_bf16_f32 v3, v3, v4
	s_nop 0
	v_addc_co_u32_e32 v19, vcc, 0, v83, vcc
	global_store_dword v[18:19], v3, off offset:64
.LBB0_512:
	s_or_b64 exec, exec, s[14:15]
	v_mul_f32_e32 v3, v21, v2
	s_waitcnt lgkmcnt(0)
	s_nop 1
	v_mov_b32_dpp v4, v3 quad_perm:[1,0,3,2] row_mask:0xf bank_mask:0xf
	s_and_saveexec_b64 s[14:15], s[12:13]
	s_cbranch_execz .LBB0_514
	v_add_co_u32_e32 v18, vcc, 0x6000, v82
	s_waitcnt lgkmcnt(0)
	v_cvt_pk_bf16_f32 v3, v3, v4
	s_nop 0
	v_addc_co_u32_e32 v19, vcc, 0, v83, vcc
	global_store_dword v[18:19], v3, off offset:128
.LBB0_514:
	s_or_b64 exec, exec, s[14:15]
	v_mul_f32_e32 v2, v5, v2
	s_nop 1
	v_mov_b32_dpp v3, v2 quad_perm:[1,0,3,2] row_mask:0xf bank_mask:0xf
	s_and_saveexec_b64 s[14:15], s[12:13]
	s_cbranch_execz .LBB0_516
	s_waitcnt lgkmcnt(0)
	v_cvt_pk_bf16_f32 v4, v2, v3
	v_add_co_u32_e32 v2, vcc, 0x6000, v82
	s_nop 1
	v_addc_co_u32_e32 v3, vcc, 0, v83, vcc
	global_store_dword v[2:3], v4, off offset:192
.LBB0_516:
	s_or_b64 exec, exec, s[14:15]
	v_rcp_f32_e32 v2, v74
	s_waitcnt lgkmcnt(0)
	v_mul_f32_e32 v3, v38, v2
	s_nop 1
	v_mov_b32_dpp v4, v3 quad_perm:[1,0,3,2] row_mask:0xf bank_mask:0xf
	s_and_saveexec_b64 s[14:15], s[12:13]
	s_cbranch_execz .LBB0_518
	s_waitcnt lgkmcnt(0)
	v_cvt_pk_bf16_f32 v3, v3, v4
	v_add_co_u32_e32 v4, vcc, 0x10000, v82
	s_nop 1
	v_addc_co_u32_e32 v5, vcc, 0, v83, vcc
	global_store_dword v[4:5], v3, off
.LBB0_518:
	s_or_b64 exec, exec, s[14:15]
	v_mul_f32_e32 v3, v54, v2
	s_waitcnt lgkmcnt(0)
	s_nop 1
	v_mov_b32_dpp v4, v3 quad_perm:[1,0,3,2] row_mask:0xf bank_mask:0xf
	s_and_saveexec_b64 s[14:15], s[12:13]
	s_cbranch_execz .LBB0_520
	s_waitcnt lgkmcnt(0)
	v_cvt_pk_bf16_f32 v3, v3, v4
	v_add_co_u32_e32 v4, vcc, 0x10000, v82
	s_nop 1
	v_addc_co_u32_e32 v5, vcc, 0, v83, vcc
	global_store_dword v[4:5], v3, off offset:64
.LBB0_520:
	s_or_b64 exec, exec, s[14:15]
	v_mul_f32_e32 v3, v22, v2
	s_waitcnt lgkmcnt(0)
	s_nop 1
	v_mov_b32_dpp v4, v3 quad_perm:[1,0,3,2] row_mask:0xf bank_mask:0xf
	s_and_saveexec_b64 s[14:15], s[12:13]
	s_cbranch_execz .LBB0_522
	s_waitcnt lgkmcnt(0)
	v_cvt_pk_bf16_f32 v3, v3, v4
	v_add_co_u32_e32 v4, vcc, 0x10000, v82
	s_nop 1
	v_addc_co_u32_e32 v5, vcc, 0, v83, vcc
	global_store_dword v[4:5], v3, off offset:128
.LBB0_522:
	s_or_b64 exec, exec, s[14:15]
	v_mul_f32_e32 v2, v6, v2
	s_nop 1
	v_mov_b32_dpp v3, v2 quad_perm:[1,0,3,2] row_mask:0xf bank_mask:0xf
	s_and_saveexec_b64 s[14:15], s[12:13]
	s_cbranch_execz .LBB0_524
	s_waitcnt lgkmcnt(0)
	v_cvt_pk_bf16_f32 v4, v2, v3
	v_add_co_u32_e32 v2, vcc, 0x10000, v82
	s_nop 1
	v_addc_co_u32_e32 v3, vcc, 0, v83, vcc
	global_store_dword v[2:3], v4, off offset:192
.LBB0_524:
	s_or_b64 exec, exec, s[14:15]
	v_rcp_f32_e32 v2, v75
	s_waitcnt lgkmcnt(0)
	v_mul_f32_e32 v3, v39, v2
	s_nop 1
	v_mov_b32_dpp v4, v3 quad_perm:[1,0,3,2] row_mask:0xf bank_mask:0xf
	s_and_saveexec_b64 s[14:15], s[12:13]
	s_cbranch_execz .LBB0_526
	s_waitcnt lgkmcnt(0)
	v_cvt_pk_bf16_f32 v3, v3, v4
	v_add_co_u32_e32 v4, vcc, 0x12000, v82
	s_nop 1
	v_addc_co_u32_e32 v5, vcc, 0, v83, vcc
	global_store_dword v[4:5], v3, off
.LBB0_526:
	s_or_b64 exec, exec, s[14:15]
	v_mul_f32_e32 v3, v55, v2
	s_waitcnt lgkmcnt(0)
	s_nop 1
	v_mov_b32_dpp v4, v3 quad_perm:[1,0,3,2] row_mask:0xf bank_mask:0xf
	s_and_saveexec_b64 s[14:15], s[12:13]
	s_cbranch_execz .LBB0_528
	s_waitcnt lgkmcnt(0)
	v_cvt_pk_bf16_f32 v3, v3, v4
	v_add_co_u32_e32 v4, vcc, 0x12000, v82
	s_nop 1
	v_addc_co_u32_e32 v5, vcc, 0, v83, vcc
	global_store_dword v[4:5], v3, off offset:64
.LBB0_528:
	s_or_b64 exec, exec, s[14:15]
	v_mul_f32_e32 v3, v23, v2
	s_waitcnt lgkmcnt(0)
	s_nop 1
	v_mov_b32_dpp v4, v3 quad_perm:[1,0,3,2] row_mask:0xf bank_mask:0xf
	s_and_saveexec_b64 s[14:15], s[12:13]
	s_cbranch_execz .LBB0_530
	s_waitcnt lgkmcnt(0)
	v_cvt_pk_bf16_f32 v3, v3, v4
	v_add_co_u32_e32 v4, vcc, 0x12000, v82
	s_nop 1
	v_addc_co_u32_e32 v5, vcc, 0, v83, vcc
	global_store_dword v[4:5], v3, off offset:128
.LBB0_530:
	s_or_b64 exec, exec, s[14:15]
	v_mul_f32_e32 v2, v7, v2
	s_nop 1
	v_mov_b32_dpp v3, v2 quad_perm:[1,0,3,2] row_mask:0xf bank_mask:0xf
	s_and_saveexec_b64 s[14:15], s[12:13]
	s_cbranch_execz .LBB0_532
	s_waitcnt lgkmcnt(0)
	v_cvt_pk_bf16_f32 v4, v2, v3
	v_add_co_u32_e32 v2, vcc, 0x12000, v82
	s_nop 1
	v_addc_co_u32_e32 v3, vcc, 0, v83, vcc
	global_store_dword v[2:3], v4, off offset:192
.LBB0_532:
	s_or_b64 exec, exec, s[14:15]
	v_rcp_f32_e32 v2, v76
	s_waitcnt lgkmcnt(0)
	v_mul_f32_e32 v3, v40, v2
	s_nop 1
	v_mov_b32_dpp v4, v3 quad_perm:[1,0,3,2] row_mask:0xf bank_mask:0xf
	s_and_saveexec_b64 s[14:15], s[12:13]
	s_cbranch_execz .LBB0_534
	s_waitcnt lgkmcnt(0)
	v_cvt_pk_bf16_f32 v3, v3, v4
	v_add_co_u32_e32 v4, vcc, 0x14000, v82
	s_nop 1
	v_addc_co_u32_e32 v5, vcc, 0, v83, vcc
	global_store_dword v[4:5], v3, off
.LBB0_534:
	s_or_b64 exec, exec, s[14:15]
	v_mul_f32_e32 v3, v56, v2
	s_waitcnt lgkmcnt(0)
	s_nop 1
	v_mov_b32_dpp v4, v3 quad_perm:[1,0,3,2] row_mask:0xf bank_mask:0xf
	s_and_saveexec_b64 s[14:15], s[12:13]
	s_cbranch_execz .LBB0_536
	s_waitcnt lgkmcnt(0)
	v_cvt_pk_bf16_f32 v3, v3, v4
	v_add_co_u32_e32 v4, vcc, 0x14000, v82
	s_nop 1
	v_addc_co_u32_e32 v5, vcc, 0, v83, vcc
	global_store_dword v[4:5], v3, off offset:64
.LBB0_536:
	s_or_b64 exec, exec, s[14:15]
	v_mul_f32_e32 v3, v24, v2
	s_waitcnt lgkmcnt(0)
	s_nop 1
	v_mov_b32_dpp v4, v3 quad_perm:[1,0,3,2] row_mask:0xf bank_mask:0xf
	s_and_saveexec_b64 s[14:15], s[12:13]
	s_cbranch_execz .LBB0_538
	s_waitcnt lgkmcnt(0)
	v_cvt_pk_bf16_f32 v3, v3, v4
	v_add_co_u32_e32 v4, vcc, 0x14000, v82
	s_nop 1
	v_addc_co_u32_e32 v5, vcc, 0, v83, vcc
	global_store_dword v[4:5], v3, off offset:128
.LBB0_538:
	s_or_b64 exec, exec, s[14:15]
	v_mul_f32_e32 v2, v8, v2
	s_nop 1
	v_mov_b32_dpp v3, v2 quad_perm:[1,0,3,2] row_mask:0xf bank_mask:0xf
	s_and_saveexec_b64 s[14:15], s[12:13]
	s_cbranch_execz .LBB0_540
	s_waitcnt lgkmcnt(0)
	v_cvt_pk_bf16_f32 v4, v2, v3
	v_add_co_u32_e32 v2, vcc, 0x14000, v82
	s_nop 1
	v_addc_co_u32_e32 v3, vcc, 0, v83, vcc
	global_store_dword v[2:3], v4, off offset:192
.LBB0_540:
	s_or_b64 exec, exec, s[14:15]
	v_rcp_f32_e32 v2, v77
	s_waitcnt lgkmcnt(0)
	v_mul_f32_e32 v3, v41, v2
	s_nop 1
	v_mov_b32_dpp v4, v3 quad_perm:[1,0,3,2] row_mask:0xf bank_mask:0xf
	s_and_saveexec_b64 s[14:15], s[12:13]
	s_cbranch_execz .LBB0_542
	s_waitcnt lgkmcnt(0)
	v_cvt_pk_bf16_f32 v3, v3, v4
	v_add_co_u32_e32 v4, vcc, 0x16000, v82
	s_nop 1
	v_addc_co_u32_e32 v5, vcc, 0, v83, vcc
	global_store_dword v[4:5], v3, off
.LBB0_542:
	s_or_b64 exec, exec, s[14:15]
	v_mul_f32_e32 v3, v57, v2
	s_waitcnt lgkmcnt(0)
	s_nop 1
	v_mov_b32_dpp v4, v3 quad_perm:[1,0,3,2] row_mask:0xf bank_mask:0xf
	s_and_saveexec_b64 s[14:15], s[12:13]
	s_cbranch_execz .LBB0_544
	s_waitcnt lgkmcnt(0)
	v_cvt_pk_bf16_f32 v3, v3, v4
	v_add_co_u32_e32 v4, vcc, 0x16000, v82
	s_nop 1
	v_addc_co_u32_e32 v5, vcc, 0, v83, vcc
	global_store_dword v[4:5], v3, off offset:64
.LBB0_544:
	s_or_b64 exec, exec, s[14:15]
	v_mul_f32_e32 v3, v25, v2
	s_waitcnt lgkmcnt(0)
	s_nop 1
	v_mov_b32_dpp v4, v3 quad_perm:[1,0,3,2] row_mask:0xf bank_mask:0xf
	s_and_saveexec_b64 s[14:15], s[12:13]
	s_cbranch_execz .LBB0_546
	s_waitcnt lgkmcnt(0)
	v_cvt_pk_bf16_f32 v3, v3, v4
	v_add_co_u32_e32 v4, vcc, 0x16000, v82
	s_nop 1
	v_addc_co_u32_e32 v5, vcc, 0, v83, vcc
	global_store_dword v[4:5], v3, off offset:128
.LBB0_546:
	s_or_b64 exec, exec, s[14:15]
	v_mul_f32_e32 v2, v9, v2
	s_nop 1
	v_mov_b32_dpp v3, v2 quad_perm:[1,0,3,2] row_mask:0xf bank_mask:0xf
	s_and_saveexec_b64 s[14:15], s[12:13]
	s_cbranch_execz .LBB0_548
	s_waitcnt lgkmcnt(0)
	v_cvt_pk_bf16_f32 v4, v2, v3
	v_add_co_u32_e32 v2, vcc, 0x16000, v82
	s_nop 1
	v_addc_co_u32_e32 v3, vcc, 0, v83, vcc
	global_store_dword v[2:3], v4, off offset:192
.LBB0_548:
	s_or_b64 exec, exec, s[14:15]
	v_rcp_f32_e32 v2, v70
	s_waitcnt lgkmcnt(0)
	v_mul_f32_e32 v3, v42, v2
	s_nop 1
	v_mov_b32_dpp v4, v3 quad_perm:[1,0,3,2] row_mask:0xf bank_mask:0xf
	s_and_saveexec_b64 s[14:15], s[12:13]
	s_cbranch_execz .LBB0_550
	s_waitcnt lgkmcnt(0)
	v_cvt_pk_bf16_f32 v3, v3, v4
	v_add_co_u32_e32 v4, vcc, 0x20000, v82
	s_nop 1
	v_addc_co_u32_e32 v5, vcc, 0, v83, vcc
	global_store_dword v[4:5], v3, off
.LBB0_550:
	s_or_b64 exec, exec, s[14:15]
	v_mul_f32_e32 v3, v58, v2
	s_waitcnt lgkmcnt(0)
	s_nop 1
	v_mov_b32_dpp v4, v3 quad_perm:[1,0,3,2] row_mask:0xf bank_mask:0xf
	s_and_saveexec_b64 s[14:15], s[12:13]
	s_cbranch_execz .LBB0_552
	s_waitcnt lgkmcnt(0)
	v_cvt_pk_bf16_f32 v3, v3, v4
	v_add_co_u32_e32 v4, vcc, 0x20000, v82
	s_nop 1
	v_addc_co_u32_e32 v5, vcc, 0, v83, vcc
	global_store_dword v[4:5], v3, off offset:64
.LBB0_552:
	s_or_b64 exec, exec, s[14:15]
	v_mul_f32_e32 v3, v26, v2
	s_waitcnt lgkmcnt(0)
	s_nop 1
	v_mov_b32_dpp v4, v3 quad_perm:[1,0,3,2] row_mask:0xf bank_mask:0xf
	s_and_saveexec_b64 s[14:15], s[12:13]
	s_cbranch_execz .LBB0_554
	s_waitcnt lgkmcnt(0)
	v_cvt_pk_bf16_f32 v3, v3, v4
	v_add_co_u32_e32 v4, vcc, 0x20000, v82
	s_nop 1
	v_addc_co_u32_e32 v5, vcc, 0, v83, vcc
	global_store_dword v[4:5], v3, off offset:128
.LBB0_554:
	s_or_b64 exec, exec, s[14:15]
	v_mul_f32_e32 v2, v10, v2
	s_nop 1
	v_mov_b32_dpp v3, v2 quad_perm:[1,0,3,2] row_mask:0xf bank_mask:0xf
	s_and_saveexec_b64 s[14:15], s[12:13]
	s_cbranch_execz .LBB0_556
	s_waitcnt lgkmcnt(0)
	v_cvt_pk_bf16_f32 v4, v2, v3
	v_add_co_u32_e32 v2, vcc, 0x20000, v82
	s_nop 1
	v_addc_co_u32_e32 v3, vcc, 0, v83, vcc
	global_store_dword v[2:3], v4, off offset:192
.LBB0_556:
	s_or_b64 exec, exec, s[14:15]
	v_rcp_f32_e32 v2, v71
	s_waitcnt lgkmcnt(0)
	v_mul_f32_e32 v3, v43, v2
	s_nop 1
	v_mov_b32_dpp v4, v3 quad_perm:[1,0,3,2] row_mask:0xf bank_mask:0xf
	s_and_saveexec_b64 s[14:15], s[12:13]
	s_cbranch_execz .LBB0_558
	s_waitcnt lgkmcnt(0)
	v_cvt_pk_bf16_f32 v3, v3, v4
	v_add_co_u32_e32 v4, vcc, 0x22000, v82
	s_nop 1
	v_addc_co_u32_e32 v5, vcc, 0, v83, vcc
	global_store_dword v[4:5], v3, off
.LBB0_558:
	s_or_b64 exec, exec, s[14:15]
	v_mul_f32_e32 v3, v59, v2
	s_waitcnt lgkmcnt(0)
	s_nop 1
	v_mov_b32_dpp v4, v3 quad_perm:[1,0,3,2] row_mask:0xf bank_mask:0xf
	s_and_saveexec_b64 s[14:15], s[12:13]
	s_cbranch_execz .LBB0_560
	s_waitcnt lgkmcnt(0)
	v_cvt_pk_bf16_f32 v3, v3, v4
	v_add_co_u32_e32 v4, vcc, 0x22000, v82
	s_nop 1
	v_addc_co_u32_e32 v5, vcc, 0, v83, vcc
	global_store_dword v[4:5], v3, off offset:64
.LBB0_560:
	s_or_b64 exec, exec, s[14:15]
	v_mul_f32_e32 v3, v27, v2
	s_waitcnt lgkmcnt(0)
	s_nop 1
	v_mov_b32_dpp v4, v3 quad_perm:[1,0,3,2] row_mask:0xf bank_mask:0xf
	s_and_saveexec_b64 s[14:15], s[12:13]
	s_cbranch_execz .LBB0_562
	s_waitcnt lgkmcnt(0)
	v_cvt_pk_bf16_f32 v3, v3, v4
	v_add_co_u32_e32 v4, vcc, 0x22000, v82
	s_nop 1
	v_addc_co_u32_e32 v5, vcc, 0, v83, vcc
	global_store_dword v[4:5], v3, off offset:128
.LBB0_562:
	s_or_b64 exec, exec, s[14:15]
	v_mul_f32_e32 v2, v11, v2
	s_nop 1
	v_mov_b32_dpp v3, v2 quad_perm:[1,0,3,2] row_mask:0xf bank_mask:0xf
	s_and_saveexec_b64 s[14:15], s[12:13]
	s_cbranch_execz .LBB0_564
	s_waitcnt lgkmcnt(0)
	v_cvt_pk_bf16_f32 v4, v2, v3
	v_add_co_u32_e32 v2, vcc, 0x22000, v82
	s_nop 1
	v_addc_co_u32_e32 v3, vcc, 0, v83, vcc
	global_store_dword v[2:3], v4, off offset:192
.LBB0_564:
	s_or_b64 exec, exec, s[14:15]
	v_rcp_f32_e32 v2, v72
	s_waitcnt lgkmcnt(0)
	v_mul_f32_e32 v3, v44, v2
	s_nop 1
	v_mov_b32_dpp v4, v3 quad_perm:[1,0,3,2] row_mask:0xf bank_mask:0xf
	s_and_saveexec_b64 s[14:15], s[12:13]
	s_cbranch_execz .LBB0_566
	s_waitcnt lgkmcnt(0)
	v_cvt_pk_bf16_f32 v3, v3, v4
	v_add_co_u32_e32 v4, vcc, 0x24000, v82
	s_nop 1
	v_addc_co_u32_e32 v5, vcc, 0, v83, vcc
	global_store_dword v[4:5], v3, off
.LBB0_566:
	s_or_b64 exec, exec, s[14:15]
	v_mul_f32_e32 v3, v60, v2
	s_waitcnt lgkmcnt(0)
	s_nop 1
	v_mov_b32_dpp v4, v3 quad_perm:[1,0,3,2] row_mask:0xf bank_mask:0xf
	s_and_saveexec_b64 s[14:15], s[12:13]
	s_cbranch_execz .LBB0_568
	s_waitcnt lgkmcnt(0)
	v_cvt_pk_bf16_f32 v3, v3, v4
	v_add_co_u32_e32 v4, vcc, 0x24000, v82
	s_nop 1
	v_addc_co_u32_e32 v5, vcc, 0, v83, vcc
	global_store_dword v[4:5], v3, off offset:64
.LBB0_568:
	s_or_b64 exec, exec, s[14:15]
	v_mul_f32_e32 v3, v28, v2
	s_waitcnt lgkmcnt(0)
	s_nop 1
	v_mov_b32_dpp v4, v3 quad_perm:[1,0,3,2] row_mask:0xf bank_mask:0xf
	s_and_saveexec_b64 s[14:15], s[12:13]
	s_cbranch_execz .LBB0_570
	s_waitcnt lgkmcnt(0)
	v_cvt_pk_bf16_f32 v3, v3, v4
	v_add_co_u32_e32 v4, vcc, 0x24000, v82
	s_nop 1
	v_addc_co_u32_e32 v5, vcc, 0, v83, vcc
	global_store_dword v[4:5], v3, off offset:128
.LBB0_570:
	s_or_b64 exec, exec, s[14:15]
	v_mul_f32_e32 v2, v12, v2
	s_nop 1
	v_mov_b32_dpp v3, v2 quad_perm:[1,0,3,2] row_mask:0xf bank_mask:0xf
	s_and_saveexec_b64 s[14:15], s[12:13]
	s_cbranch_execz .LBB0_572
	s_waitcnt lgkmcnt(0)
	v_cvt_pk_bf16_f32 v4, v2, v3
	v_add_co_u32_e32 v2, vcc, 0x24000, v82
	s_nop 1
	v_addc_co_u32_e32 v3, vcc, 0, v83, vcc
	global_store_dword v[2:3], v4, off offset:192
.LBB0_572:
	s_or_b64 exec, exec, s[14:15]
	v_rcp_f32_e32 v2, v73
	s_waitcnt lgkmcnt(0)
	v_mul_f32_e32 v3, v45, v2
	s_nop 1
	v_mov_b32_dpp v4, v3 quad_perm:[1,0,3,2] row_mask:0xf bank_mask:0xf
	s_and_saveexec_b64 s[14:15], s[12:13]
	s_cbranch_execz .LBB0_574
	s_waitcnt lgkmcnt(0)
	v_cvt_pk_bf16_f32 v3, v3, v4
	v_add_co_u32_e32 v4, vcc, 0x26000, v82
	s_nop 1
	v_addc_co_u32_e32 v5, vcc, 0, v83, vcc
	global_store_dword v[4:5], v3, off
.LBB0_574:
	s_or_b64 exec, exec, s[14:15]
	v_mul_f32_e32 v3, v61, v2
	s_waitcnt lgkmcnt(0)
	s_nop 1
	v_mov_b32_dpp v4, v3 quad_perm:[1,0,3,2] row_mask:0xf bank_mask:0xf
	s_and_saveexec_b64 s[14:15], s[12:13]
	s_cbranch_execz .LBB0_576
	s_waitcnt lgkmcnt(0)
	v_cvt_pk_bf16_f32 v3, v3, v4
	v_add_co_u32_e32 v4, vcc, 0x26000, v82
	s_nop 1
	v_addc_co_u32_e32 v5, vcc, 0, v83, vcc
	global_store_dword v[4:5], v3, off offset:64
.LBB0_576:
	s_or_b64 exec, exec, s[14:15]
	v_mul_f32_e32 v3, v29, v2
	s_waitcnt lgkmcnt(0)
	s_nop 1
	v_mov_b32_dpp v4, v3 quad_perm:[1,0,3,2] row_mask:0xf bank_mask:0xf
	s_and_saveexec_b64 s[14:15], s[12:13]
	s_cbranch_execz .LBB0_578
	s_waitcnt lgkmcnt(0)
	v_cvt_pk_bf16_f32 v3, v3, v4
	v_add_co_u32_e32 v4, vcc, 0x26000, v82
	s_nop 1
	v_addc_co_u32_e32 v5, vcc, 0, v83, vcc
	global_store_dword v[4:5], v3, off offset:128
.LBB0_578:
	s_or_b64 exec, exec, s[14:15]
	v_mul_f32_e32 v2, v13, v2
	s_nop 1
	v_mov_b32_dpp v3, v2 quad_perm:[1,0,3,2] row_mask:0xf bank_mask:0xf
	s_and_saveexec_b64 s[14:15], s[12:13]
	s_cbranch_execz .LBB0_580
	s_waitcnt lgkmcnt(0)
	v_cvt_pk_bf16_f32 v4, v2, v3
	v_add_co_u32_e32 v2, vcc, 0x26000, v82
	s_nop 1
	v_addc_co_u32_e32 v3, vcc, 0, v83, vcc
	global_store_dword v[2:3], v4, off offset:192
.LBB0_580:
	s_or_b64 exec, exec, s[14:15]
	v_rcp_f32_e32 v2, v66
	s_waitcnt lgkmcnt(0)
	v_mul_f32_e32 v3, v46, v2
	s_nop 1
	v_mov_b32_dpp v4, v3 quad_perm:[1,0,3,2] row_mask:0xf bank_mask:0xf
	s_and_saveexec_b64 s[14:15], s[12:13]
	s_cbranch_execz .LBB0_582
	s_waitcnt lgkmcnt(0)
	v_cvt_pk_bf16_f32 v3, v3, v4
	v_add_co_u32_e32 v4, vcc, 0x30000, v82
	s_nop 1
	v_addc_co_u32_e32 v5, vcc, 0, v83, vcc
	global_store_dword v[4:5], v3, off
.LBB0_582:
	s_or_b64 exec, exec, s[14:15]
	v_mul_f32_e32 v3, v62, v2
	s_waitcnt lgkmcnt(0)
	s_nop 1
	v_mov_b32_dpp v4, v3 quad_perm:[1,0,3,2] row_mask:0xf bank_mask:0xf
	s_and_saveexec_b64 s[14:15], s[12:13]
	s_cbranch_execz .LBB0_584
	s_waitcnt lgkmcnt(0)
	v_cvt_pk_bf16_f32 v3, v3, v4
	v_add_co_u32_e32 v4, vcc, 0x30000, v82
	s_nop 1
	v_addc_co_u32_e32 v5, vcc, 0, v83, vcc
	global_store_dword v[4:5], v3, off offset:64
.LBB0_584:
	s_or_b64 exec, exec, s[14:15]
	v_mul_f32_e32 v3, v30, v2
	s_waitcnt lgkmcnt(0)
	s_nop 1
	v_mov_b32_dpp v4, v3 quad_perm:[1,0,3,2] row_mask:0xf bank_mask:0xf
	s_and_saveexec_b64 s[14:15], s[12:13]
	s_cbranch_execz .LBB0_586
	s_waitcnt lgkmcnt(0)
	v_cvt_pk_bf16_f32 v3, v3, v4
	v_add_co_u32_e32 v4, vcc, 0x30000, v82
	s_nop 1
	v_addc_co_u32_e32 v5, vcc, 0, v83, vcc
	global_store_dword v[4:5], v3, off offset:128
.LBB0_586:
	s_or_b64 exec, exec, s[14:15]
	v_mul_f32_e32 v2, v14, v2
	s_nop 1
	v_mov_b32_dpp v3, v2 quad_perm:[1,0,3,2] row_mask:0xf bank_mask:0xf
	s_and_saveexec_b64 s[14:15], s[12:13]
	s_cbranch_execz .LBB0_588
	s_waitcnt lgkmcnt(0)
	v_cvt_pk_bf16_f32 v4, v2, v3
	v_add_co_u32_e32 v2, vcc, 0x30000, v82
	s_nop 1
	v_addc_co_u32_e32 v3, vcc, 0, v83, vcc
	global_store_dword v[2:3], v4, off offset:192
.LBB0_588:
	s_or_b64 exec, exec, s[14:15]
	v_rcp_f32_e32 v2, v67
	s_waitcnt lgkmcnt(0)
	v_mul_f32_e32 v3, v47, v2
	s_nop 1
	v_mov_b32_dpp v4, v3 quad_perm:[1,0,3,2] row_mask:0xf bank_mask:0xf
	s_and_saveexec_b64 s[14:15], s[12:13]
	s_cbranch_execz .LBB0_590
	s_waitcnt lgkmcnt(0)
	v_cvt_pk_bf16_f32 v3, v3, v4
	v_add_co_u32_e32 v4, vcc, 0x32000, v82
	s_nop 1
	v_addc_co_u32_e32 v5, vcc, 0, v83, vcc
	global_store_dword v[4:5], v3, off
.LBB0_590:
	s_or_b64 exec, exec, s[14:15]
	v_mul_f32_e32 v3, v63, v2
	s_waitcnt lgkmcnt(0)
	s_nop 1
	v_mov_b32_dpp v4, v3 quad_perm:[1,0,3,2] row_mask:0xf bank_mask:0xf
	s_and_saveexec_b64 s[14:15], s[12:13]
	s_cbranch_execz .LBB0_592
	s_waitcnt lgkmcnt(0)
	v_cvt_pk_bf16_f32 v3, v3, v4
	v_add_co_u32_e32 v4, vcc, 0x32000, v82
	s_nop 1
	v_addc_co_u32_e32 v5, vcc, 0, v83, vcc
	global_store_dword v[4:5], v3, off offset:64
.LBB0_592:
	s_or_b64 exec, exec, s[14:15]
	v_mul_f32_e32 v3, v31, v2
	s_waitcnt lgkmcnt(0)
	s_nop 1
	v_mov_b32_dpp v4, v3 quad_perm:[1,0,3,2] row_mask:0xf bank_mask:0xf
	s_and_saveexec_b64 s[14:15], s[12:13]
	s_cbranch_execz .LBB0_594
	s_waitcnt lgkmcnt(0)
	v_cvt_pk_bf16_f32 v3, v3, v4
	v_add_co_u32_e32 v4, vcc, 0x32000, v82
	s_nop 1
	v_addc_co_u32_e32 v5, vcc, 0, v83, vcc
	global_store_dword v[4:5], v3, off offset:128
.LBB0_594:
	s_or_b64 exec, exec, s[14:15]
	v_mul_f32_e32 v2, v15, v2
	s_nop 1
	v_mov_b32_dpp v3, v2 quad_perm:[1,0,3,2] row_mask:0xf bank_mask:0xf
	s_and_saveexec_b64 s[14:15], s[12:13]
	s_cbranch_execz .LBB0_596
	s_waitcnt lgkmcnt(0)
	v_cvt_pk_bf16_f32 v4, v2, v3
	v_add_co_u32_e32 v2, vcc, 0x32000, v82
	s_nop 1
	v_addc_co_u32_e32 v3, vcc, 0, v83, vcc
	global_store_dword v[2:3], v4, off offset:192
.LBB0_596:
	s_or_b64 exec, exec, s[14:15]
	v_rcp_f32_e32 v2, v68
	s_waitcnt lgkmcnt(0)
	v_mul_f32_e32 v3, v48, v2
	s_nop 1
	v_mov_b32_dpp v4, v3 quad_perm:[1,0,3,2] row_mask:0xf bank_mask:0xf
	s_and_saveexec_b64 s[14:15], s[12:13]
	s_cbranch_execz .LBB0_598
	s_waitcnt lgkmcnt(0)
	v_cvt_pk_bf16_f32 v3, v3, v4
	v_add_co_u32_e32 v4, vcc, 0x34000, v82
	s_nop 1
	v_addc_co_u32_e32 v5, vcc, 0, v83, vcc
	global_store_dword v[4:5], v3, off
.LBB0_598:
	s_or_b64 exec, exec, s[14:15]
	v_mul_f32_e32 v3, v64, v2
	s_waitcnt lgkmcnt(0)
	s_nop 1
	v_mov_b32_dpp v4, v3 quad_perm:[1,0,3,2] row_mask:0xf bank_mask:0xf
	s_and_saveexec_b64 s[14:15], s[12:13]
	s_cbranch_execz .LBB0_600
	s_waitcnt lgkmcnt(0)
	v_cvt_pk_bf16_f32 v3, v3, v4
	v_add_co_u32_e32 v4, vcc, 0x34000, v82
	s_nop 1
	v_addc_co_u32_e32 v5, vcc, 0, v83, vcc
	global_store_dword v[4:5], v3, off offset:64
.LBB0_600:
	s_or_b64 exec, exec, s[14:15]
	v_mul_f32_e32 v3, v32, v2
	s_waitcnt lgkmcnt(0)
	s_nop 1
	v_mov_b32_dpp v4, v3 quad_perm:[1,0,3,2] row_mask:0xf bank_mask:0xf
	s_and_saveexec_b64 s[14:15], s[12:13]
	s_cbranch_execz .LBB0_602
	s_waitcnt lgkmcnt(0)
	v_cvt_pk_bf16_f32 v3, v3, v4
	v_add_co_u32_e32 v4, vcc, 0x34000, v82
	s_nop 1
	v_addc_co_u32_e32 v5, vcc, 0, v83, vcc
	global_store_dword v[4:5], v3, off offset:128
.LBB0_602:
	s_or_b64 exec, exec, s[14:15]
	v_mul_f32_e32 v2, v16, v2
	s_nop 1
	v_mov_b32_dpp v3, v2 quad_perm:[1,0,3,2] row_mask:0xf bank_mask:0xf
	s_and_saveexec_b64 s[14:15], s[12:13]
	s_cbranch_execz .LBB0_604
	s_waitcnt lgkmcnt(0)
	v_cvt_pk_bf16_f32 v4, v2, v3
	v_add_co_u32_e32 v2, vcc, 0x34000, v82
	s_nop 1
	v_addc_co_u32_e32 v3, vcc, 0, v83, vcc
	global_store_dword v[2:3], v4, off offset:192
.LBB0_604:
	s_or_b64 exec, exec, s[14:15]
	v_rcp_f32_e32 v2, v69
	s_waitcnt lgkmcnt(0)
	v_mul_f32_e32 v3, v49, v2
	s_nop 1
	v_mov_b32_dpp v4, v3 quad_perm:[1,0,3,2] row_mask:0xf bank_mask:0xf
	s_and_saveexec_b64 s[14:15], s[12:13]
	s_cbranch_execz .LBB0_606
	s_waitcnt lgkmcnt(0)
	v_cvt_pk_bf16_f32 v3, v3, v4
	v_add_co_u32_e32 v4, vcc, 0x36000, v82
	s_nop 1
	v_addc_co_u32_e32 v5, vcc, 0, v83, vcc
	global_store_dword v[4:5], v3, off
.LBB0_606:
	s_or_b64 exec, exec, s[14:15]
	v_mul_f32_e32 v3, v65, v2
	s_waitcnt lgkmcnt(0)
	s_nop 1
	v_mov_b32_dpp v4, v3 quad_perm:[1,0,3,2] row_mask:0xf bank_mask:0xf
	s_and_saveexec_b64 s[14:15], s[12:13]
	s_cbranch_execz .LBB0_608
	s_waitcnt lgkmcnt(0)
	v_cvt_pk_bf16_f32 v3, v3, v4
	v_add_co_u32_e32 v4, vcc, 0x36000, v82
	s_nop 1
	v_addc_co_u32_e32 v5, vcc, 0, v83, vcc
	global_store_dword v[4:5], v3, off offset:64
.LBB0_608:
	s_or_b64 exec, exec, s[14:15]
	v_mul_f32_e32 v3, v33, v2
	s_waitcnt lgkmcnt(0)
	s_nop 1
	v_mov_b32_dpp v4, v3 quad_perm:[1,0,3,2] row_mask:0xf bank_mask:0xf
	s_and_saveexec_b64 s[14:15], s[12:13]
	s_cbranch_execz .LBB0_610
	s_waitcnt lgkmcnt(0)
	v_cvt_pk_bf16_f32 v3, v3, v4
	v_add_co_u32_e32 v4, vcc, 0x36000, v82
	s_nop 1
	v_addc_co_u32_e32 v5, vcc, 0, v83, vcc
	global_store_dword v[4:5], v3, off offset:128
.LBB0_610:
	s_or_b64 exec, exec, s[14:15]
	v_mul_f32_e32 v2, v17, v2
	s_nop 1
	v_mov_b32_dpp v3, v2 quad_perm:[1,0,3,2] row_mask:0xf bank_mask:0xf
	s_and_saveexec_b64 s[14:15], s[12:13]
	s_cbranch_execz .LBB0_454
	s_waitcnt lgkmcnt(0)
	v_cvt_pk_bf16_f32 v4, v2, v3
	v_add_co_u32_e32 v2, vcc, 0x36000, v82
	s_nop 1
	v_addc_co_u32_e32 v3, vcc, 0, v83, vcc
	global_store_dword v[2:3], v4, off offset:192
	s_branch .LBB0_454

.LBB0_653:
	s_or_b64 exec, exec, s[18:19]
	ds_read_b128 v[78:81], v180
	ds_read_b128 v[74:77], v180 offset:32
	s_mul_hi_i32 s0, s71, 0x1800
	s_mulk_i32 s71, 0x1800
	s_add_u32 s1, s58, s71
	s_waitcnt lgkmcnt(1)
	v_rcp_f32_e32 v78, v78
	s_addc_u32 s0, s59, s0
	s_lshl_b32 s18, s41, 8
	s_add_u32 s1, s1, s18
	v_mul_f32_e32 v50, v50, v78
	s_addc_u32 s0, s0, 0
	ds_read_b128 v[70:73], v180 offset:64
	ds_read_b128 v[66:69], v180 offset:96
	s_mul_hi_i32 s19, s70, 0x1800
	s_mulk_i32 s70, 0x1800
	s_nop 1
	v_mov_b32_dpp v84, v50 quad_perm:[1,0,3,2] row_mask:0xf bank_mask:0xf
	s_add_u32 s18, s1, s70
	s_addc_u32 s19, s0, s19
	v_and_b32_e32 v82, 1, v172
	v_lshlrev_b32_e32 v162, 1, v174
	v_cmp_eq_u32_e64 s[0:1], 0, v82
	v_lshl_add_u64 v[82:83], s[18:19], 0, v[162:163]
	v_mul_u32_u24_e32 v162, 0x6000, v173
	v_lshl_add_u64 v[82:83], v[82:83], 0, v[162:163]
	s_and_saveexec_b64 s[18:19], s[0:1]
	s_cbranch_execz .LBB0_655
	s_waitcnt lgkmcnt(0)
	v_cvt_pk_bf16_f32 v50, v50, v84
	global_store_dword v[82:83], v50, off
.LBB0_655:
	s_or_b64 exec, exec, s[18:19]
	v_mul_f32_e32 v34, v34, v78
	s_nop 1
	v_mov_b32_dpp v50, v34 quad_perm:[1,0,3,2] row_mask:0xf bank_mask:0xf
	s_and_saveexec_b64 s[18:19], s[0:1]
	s_cbranch_execz .LBB0_657
	s_waitcnt lgkmcnt(0)
	v_cvt_pk_bf16_f32 v34, v34, v50
	global_store_dword v[82:83], v34, off offset:64
.LBB0_657:
	s_or_b64 exec, exec, s[18:19]
	v_mul_f32_e32 v18, v18, v78
	s_nop 1
	v_mov_b32_dpp v34, v18 quad_perm:[1,0,3,2] row_mask:0xf bank_mask:0xf
	s_and_saveexec_b64 s[18:19], s[0:1]
	s_cbranch_execz .LBB0_659
	s_waitcnt lgkmcnt(0)
	v_cvt_pk_bf16_f32 v18, v18, v34
	global_store_dword v[82:83], v18, off offset:128
.LBB0_659:
	s_or_b64 exec, exec, s[18:19]
	v_mul_f32_e32 v2, v2, v78
	s_nop 1
	v_mov_b32_dpp v18, v2 quad_perm:[1,0,3,2] row_mask:0xf bank_mask:0xf
	s_and_saveexec_b64 s[18:19], s[0:1]
	s_cbranch_execz .LBB0_661
	s_waitcnt lgkmcnt(0)
	v_cvt_pk_bf16_f32 v2, v2, v18
	global_store_dword v[82:83], v2, off offset:192
.LBB0_661:
	s_or_b64 exec, exec, s[18:19]
	v_rcp_f32_e32 v2, v79
	s_waitcnt lgkmcnt(0)
	v_mul_f32_e32 v18, v51, v2
	s_nop 1
	v_mov_b32_dpp v34, v18 quad_perm:[1,0,3,2] row_mask:0xf bank_mask:0xf
	s_and_saveexec_b64 s[18:19], s[0:1]
	s_cbranch_execz .LBB0_663
	v_add_co_u32_e32 v50, vcc, 0x1000, v82
	s_waitcnt lgkmcnt(0)
	v_cvt_pk_bf16_f32 v18, v18, v34
	s_nop 0
	v_addc_co_u32_e32 v51, vcc, 0, v83, vcc
	global_store_dword v[50:51], v18, off offset:2048
.LBB0_663:
	s_or_b64 exec, exec, s[18:19]
	v_mul_f32_e32 v18, v35, v2
	s_waitcnt lgkmcnt(0)
	s_nop 1
	v_mov_b32_dpp v34, v18 quad_perm:[1,0,3,2] row_mask:0xf bank_mask:0xf
	s_and_saveexec_b64 s[18:19], s[0:1]
	s_cbranch_execz .LBB0_665
	s_waitcnt lgkmcnt(0)
	v_cvt_pk_bf16_f32 v18, v18, v34
	v_add_co_u32_e32 v34, vcc, 0x1000, v82
	s_nop 1
	v_addc_co_u32_e32 v35, vcc, 0, v83, vcc
	global_store_dword v[34:35], v18, off offset:2112
.LBB0_665:
	s_or_b64 exec, exec, s[18:19]
	v_mul_f32_e32 v18, v19, v2
	s_nop 1
	v_mov_b32_dpp v19, v18 quad_perm:[1,0,3,2] row_mask:0xf bank_mask:0xf
	s_and_saveexec_b64 s[18:19], s[0:1]
	s_cbranch_execz .LBB0_667
	s_waitcnt lgkmcnt(0)
	v_cvt_pk_bf16_f32 v34, v18, v19
	v_add_co_u32_e32 v18, vcc, 0x1000, v82
	s_nop 1
	v_addc_co_u32_e32 v19, vcc, 0, v83, vcc
	global_store_dword v[18:19], v34, off offset:2176
.LBB0_667:
	s_or_b64 exec, exec, s[18:19]
	v_mul_f32_e32 v2, v3, v2
	s_nop 1
	v_mov_b32_dpp v3, v2 quad_perm:[1,0,3,2] row_mask:0xf bank_mask:0xf
	s_and_saveexec_b64 s[18:19], s[0:1]
	s_cbranch_execz .LBB0_669
	s_waitcnt lgkmcnt(0)
	v_cvt_pk_bf16_f32 v18, v2, v3
	v_add_co_u32_e32 v2, vcc, 0x1000, v82
	s_nop 1
	v_addc_co_u32_e32 v3, vcc, 0, v83, vcc
	global_store_dword v[2:3], v18, off offset:2240
.LBB0_669:
	s_or_b64 exec, exec, s[18:19]
	v_rcp_f32_e32 v2, v80
	s_waitcnt lgkmcnt(0)
	v_mul_f32_e32 v3, v52, v2
	s_nop 1
	v_mov_b32_dpp v18, v3 quad_perm:[1,0,3,2] row_mask:0xf bank_mask:0xf
	s_and_saveexec_b64 s[18:19], s[0:1]
	s_cbranch_execz .LBB0_671
	s_waitcnt lgkmcnt(0)
	v_cvt_pk_bf16_f32 v3, v3, v18
	v_add_co_u32_e32 v18, vcc, 0x3000, v82
	s_nop 1
	v_addc_co_u32_e32 v19, vcc, 0, v83, vcc
	global_store_dword v[18:19], v3, off
.LBB0_671:
	s_or_b64 exec, exec, s[18:19]
	v_mul_f32_e32 v3, v36, v2
	s_waitcnt lgkmcnt(0)
	s_nop 1
	v_mov_b32_dpp v18, v3 quad_perm:[1,0,3,2] row_mask:0xf bank_mask:0xf
	s_and_saveexec_b64 s[18:19], s[0:1]
	s_cbranch_execz .LBB0_673
	s_waitcnt lgkmcnt(0)
	v_cvt_pk_bf16_f32 v3, v3, v18
	v_add_co_u32_e32 v18, vcc, 0x3000, v82
	s_nop 1
	v_addc_co_u32_e32 v19, vcc, 0, v83, vcc
	global_store_dword v[18:19], v3, off offset:64
.LBB0_673:
	s_or_b64 exec, exec, s[18:19]
	v_mul_f32_e32 v3, v20, v2
	s_waitcnt lgkmcnt(0)
	s_nop 1
	v_mov_b32_dpp v18, v3 quad_perm:[1,0,3,2] row_mask:0xf bank_mask:0xf
	s_and_saveexec_b64 s[18:19], s[0:1]
	s_cbranch_execz .LBB0_675
	s_waitcnt lgkmcnt(0)
	v_cvt_pk_bf16_f32 v3, v3, v18
	v_add_co_u32_e32 v18, vcc, 0x3000, v82
	s_nop 1
	v_addc_co_u32_e32 v19, vcc, 0, v83, vcc
	global_store_dword v[18:19], v3, off offset:128
.LBB0_675:
	s_or_b64 exec, exec, s[18:19]
	v_mul_f32_e32 v2, v4, v2
	s_nop 1
	v_mov_b32_dpp v3, v2 quad_perm:[1,0,3,2] row_mask:0xf bank_mask:0xf
	s_and_saveexec_b64 s[18:19], s[0:1]
	s_cbranch_execz .LBB0_677
	s_waitcnt lgkmcnt(0)
	v_cvt_pk_bf16_f32 v4, v2, v3
	v_add_co_u32_e32 v2, vcc, 0x3000, v82
	s_nop 1
	v_addc_co_u32_e32 v3, vcc, 0, v83, vcc
	global_store_dword v[2:3], v4, off offset:192
.LBB0_677:
	s_or_b64 exec, exec, s[18:19]
	v_rcp_f32_e32 v2, v81
	s_waitcnt lgkmcnt(0)
	v_mul_f32_e32 v3, v53, v2
	s_nop 1
	v_mov_b32_dpp v4, v3 quad_perm:[1,0,3,2] row_mask:0xf bank_mask:0xf
	s_and_saveexec_b64 s[18:19], s[0:1]
	s_cbranch_execz .LBB0_679
	v_add_co_u32_e32 v18, vcc, 0x4000, v82
	s_waitcnt lgkmcnt(0)
	v_cvt_pk_bf16_f32 v3, v3, v4
	s_nop 0
	v_addc_co_u32_e32 v19, vcc, 0, v83, vcc
	global_store_dword v[18:19], v3, off offset:2048
.LBB0_679:
	s_or_b64 exec, exec, s[18:19]
	v_mul_f32_e32 v3, v37, v2
	s_waitcnt lgkmcnt(0)
	s_nop 1
	v_mov_b32_dpp v4, v3 quad_perm:[1,0,3,2] row_mask:0xf bank_mask:0xf
	s_and_saveexec_b64 s[18:19], s[0:1]
	s_cbranch_execz .LBB0_681
	v_add_co_u32_e32 v18, vcc, 0x4000, v82
	s_waitcnt lgkmcnt(0)
	v_cvt_pk_bf16_f32 v3, v3, v4
	s_nop 0
	v_addc_co_u32_e32 v19, vcc, 0, v83, vcc
	global_store_dword v[18:19], v3, off offset:2112
.LBB0_681:
	s_or_b64 exec, exec, s[18:19]
	v_mul_f32_e32 v3, v21, v2
	s_waitcnt lgkmcnt(0)
	s_nop 1
	v_mov_b32_dpp v4, v3 quad_perm:[1,0,3,2] row_mask:0xf bank_mask:0xf
	s_and_saveexec_b64 s[18:19], s[0:1]
	s_cbranch_execz .LBB0_683
	v_add_co_u32_e32 v18, vcc, 0x4000, v82
	s_waitcnt lgkmcnt(0)
	v_cvt_pk_bf16_f32 v3, v3, v4
	s_nop 0
	v_addc_co_u32_e32 v19, vcc, 0, v83, vcc
	global_store_dword v[18:19], v3, off offset:2176
.LBB0_683:
	s_or_b64 exec, exec, s[18:19]
	v_mul_f32_e32 v2, v5, v2
	s_nop 1
	v_mov_b32_dpp v3, v2 quad_perm:[1,0,3,2] row_mask:0xf bank_mask:0xf
	s_and_saveexec_b64 s[18:19], s[0:1]
	s_cbranch_execz .LBB0_685
	s_waitcnt lgkmcnt(0)
	v_cvt_pk_bf16_f32 v4, v2, v3
	v_add_co_u32_e32 v2, vcc, 0x4000, v82
	s_nop 1
	v_addc_co_u32_e32 v3, vcc, 0, v83, vcc
	global_store_dword v[2:3], v4, off offset:2240
.LBB0_685:
	s_or_b64 exec, exec, s[18:19]
	v_rcp_f32_e32 v2, v74
	s_waitcnt lgkmcnt(0)
	v_mul_f32_e32 v3, v54, v2
	s_nop 1
	v_mov_b32_dpp v4, v3 quad_perm:[1,0,3,2] row_mask:0xf bank_mask:0xf
	s_and_saveexec_b64 s[18:19], s[0:1]
	s_cbranch_execz .LBB0_687
	s_waitcnt lgkmcnt(0)
	v_cvt_pk_bf16_f32 v3, v3, v4
	v_add_co_u32_e32 v4, vcc, 0xc000, v82
	s_nop 1
	v_addc_co_u32_e32 v5, vcc, 0, v83, vcc
	global_store_dword v[4:5], v3, off
.LBB0_687:
	s_or_b64 exec, exec, s[18:19]
	v_mul_f32_e32 v3, v38, v2
	s_waitcnt lgkmcnt(0)
	s_nop 1
	v_mov_b32_dpp v4, v3 quad_perm:[1,0,3,2] row_mask:0xf bank_mask:0xf
	s_and_saveexec_b64 s[18:19], s[0:1]
	s_cbranch_execz .LBB0_689
	s_waitcnt lgkmcnt(0)
	v_cvt_pk_bf16_f32 v3, v3, v4
	v_add_co_u32_e32 v4, vcc, 0xc000, v82
	s_nop 1
	v_addc_co_u32_e32 v5, vcc, 0, v83, vcc
	global_store_dword v[4:5], v3, off offset:64
.LBB0_689:
	s_or_b64 exec, exec, s[18:19]
	v_mul_f32_e32 v3, v22, v2
	s_waitcnt lgkmcnt(0)
	s_nop 1
	v_mov_b32_dpp v4, v3 quad_perm:[1,0,3,2] row_mask:0xf bank_mask:0xf
	s_and_saveexec_b64 s[18:19], s[0:1]
	s_cbranch_execz .LBB0_691
	s_waitcnt lgkmcnt(0)
	v_cvt_pk_bf16_f32 v3, v3, v4
	v_add_co_u32_e32 v4, vcc, 0xc000, v82
	s_nop 1
	v_addc_co_u32_e32 v5, vcc, 0, v83, vcc
	global_store_dword v[4:5], v3, off offset:128
.LBB0_691:
	s_or_b64 exec, exec, s[18:19]
	v_mul_f32_e32 v2, v6, v2
	s_nop 1
	v_mov_b32_dpp v3, v2 quad_perm:[1,0,3,2] row_mask:0xf bank_mask:0xf
	s_and_saveexec_b64 s[18:19], s[0:1]
	s_cbranch_execz .LBB0_693
	s_waitcnt lgkmcnt(0)
	v_cvt_pk_bf16_f32 v4, v2, v3
	v_add_co_u32_e32 v2, vcc, 0xc000, v82
	s_nop 1
	v_addc_co_u32_e32 v3, vcc, 0, v83, vcc
	global_store_dword v[2:3], v4, off offset:192
.LBB0_693:
	s_or_b64 exec, exec, s[18:19]
	v_rcp_f32_e32 v2, v75
	s_waitcnt lgkmcnt(0)
	v_mul_f32_e32 v3, v55, v2
	s_nop 1
	v_mov_b32_dpp v4, v3 quad_perm:[1,0,3,2] row_mask:0xf bank_mask:0xf
	s_and_saveexec_b64 s[18:19], s[0:1]
	s_cbranch_execz .LBB0_695
	s_waitcnt lgkmcnt(0)
	v_cvt_pk_bf16_f32 v3, v3, v4
	v_add_co_u32_e32 v4, vcc, 0xd000, v82
	s_nop 1
	v_addc_co_u32_e32 v5, vcc, 0, v83, vcc
	global_store_dword v[4:5], v3, off offset:2048
.LBB0_695:
	s_or_b64 exec, exec, s[18:19]
	v_mul_f32_e32 v3, v39, v2
	s_waitcnt lgkmcnt(0)
	s_nop 1
	v_mov_b32_dpp v4, v3 quad_perm:[1,0,3,2] row_mask:0xf bank_mask:0xf
	s_and_saveexec_b64 s[18:19], s[0:1]
	s_cbranch_execz .LBB0_697
	s_waitcnt lgkmcnt(0)
	v_cvt_pk_bf16_f32 v3, v3, v4
	v_add_co_u32_e32 v4, vcc, 0xd000, v82
	s_nop 1
	v_addc_co_u32_e32 v5, vcc, 0, v83, vcc
	global_store_dword v[4:5], v3, off offset:2112
.LBB0_697:
	s_or_b64 exec, exec, s[18:19]
	v_mul_f32_e32 v3, v23, v2
	s_waitcnt lgkmcnt(0)
	s_nop 1
	v_mov_b32_dpp v4, v3 quad_perm:[1,0,3,2] row_mask:0xf bank_mask:0xf
	s_and_saveexec_b64 s[18:19], s[0:1]
	s_cbranch_execz .LBB0_699
	s_waitcnt lgkmcnt(0)
	v_cvt_pk_bf16_f32 v3, v3, v4
	v_add_co_u32_e32 v4, vcc, 0xd000, v82
	s_nop 1
	v_addc_co_u32_e32 v5, vcc, 0, v83, vcc
	global_store_dword v[4:5], v3, off offset:2176
.LBB0_699:
	s_or_b64 exec, exec, s[18:19]
	v_mul_f32_e32 v2, v7, v2
	s_nop 1
	v_mov_b32_dpp v3, v2 quad_perm:[1,0,3,2] row_mask:0xf bank_mask:0xf
	s_and_saveexec_b64 s[18:19], s[0:1]
	s_cbranch_execz .LBB0_701
	s_waitcnt lgkmcnt(0)
	v_cvt_pk_bf16_f32 v4, v2, v3
	v_add_co_u32_e32 v2, vcc, 0xd000, v82
	s_nop 1
	v_addc_co_u32_e32 v3, vcc, 0, v83, vcc
	global_store_dword v[2:3], v4, off offset:2240
.LBB0_701:
	s_or_b64 exec, exec, s[18:19]
	v_rcp_f32_e32 v2, v76
	s_waitcnt lgkmcnt(0)
	v_mul_f32_e32 v3, v56, v2
	s_nop 1
	v_mov_b32_dpp v4, v3 quad_perm:[1,0,3,2] row_mask:0xf bank_mask:0xf
	s_and_saveexec_b64 s[18:19], s[0:1]
	s_cbranch_execz .LBB0_703
	s_waitcnt lgkmcnt(0)
	v_cvt_pk_bf16_f32 v3, v3, v4
	v_add_co_u32_e32 v4, vcc, 0xf000, v82
	s_nop 1
	v_addc_co_u32_e32 v5, vcc, 0, v83, vcc
	global_store_dword v[4:5], v3, off
.LBB0_703:
	s_or_b64 exec, exec, s[18:19]
	v_mul_f32_e32 v3, v40, v2
	s_waitcnt lgkmcnt(0)
	s_nop 1
	v_mov_b32_dpp v4, v3 quad_perm:[1,0,3,2] row_mask:0xf bank_mask:0xf
	s_and_saveexec_b64 s[18:19], s[0:1]
	s_cbranch_execz .LBB0_705
	s_waitcnt lgkmcnt(0)
	v_cvt_pk_bf16_f32 v3, v3, v4
	v_add_co_u32_e32 v4, vcc, 0xf000, v82
	s_nop 1
	v_addc_co_u32_e32 v5, vcc, 0, v83, vcc
	global_store_dword v[4:5], v3, off offset:64
.LBB0_705:
	s_or_b64 exec, exec, s[18:19]
	v_mul_f32_e32 v3, v24, v2
	s_waitcnt lgkmcnt(0)
	s_nop 1
	v_mov_b32_dpp v4, v3 quad_perm:[1,0,3,2] row_mask:0xf bank_mask:0xf
	s_and_saveexec_b64 s[18:19], s[0:1]
	s_cbranch_execz .LBB0_707
	s_waitcnt lgkmcnt(0)
	v_cvt_pk_bf16_f32 v3, v3, v4
	v_add_co_u32_e32 v4, vcc, 0xf000, v82
	s_nop 1
	v_addc_co_u32_e32 v5, vcc, 0, v83, vcc
	global_store_dword v[4:5], v3, off offset:128
.LBB0_707:
	s_or_b64 exec, exec, s[18:19]
	v_mul_f32_e32 v2, v8, v2
	s_nop 1
	v_mov_b32_dpp v3, v2 quad_perm:[1,0,3,2] row_mask:0xf bank_mask:0xf
	s_and_saveexec_b64 s[18:19], s[0:1]
	s_cbranch_execz .LBB0_709
	s_waitcnt lgkmcnt(0)
	v_cvt_pk_bf16_f32 v4, v2, v3
	v_add_co_u32_e32 v2, vcc, 0xf000, v82
	s_nop 1
	v_addc_co_u32_e32 v3, vcc, 0, v83, vcc
	global_store_dword v[2:3], v4, off offset:192
.LBB0_709:
	s_or_b64 exec, exec, s[18:19]
	v_rcp_f32_e32 v2, v77
	s_waitcnt lgkmcnt(0)
	v_mul_f32_e32 v3, v57, v2
	s_nop 1
	v_mov_b32_dpp v4, v3 quad_perm:[1,0,3,2] row_mask:0xf bank_mask:0xf
	s_and_saveexec_b64 s[18:19], s[0:1]
	s_cbranch_execz .LBB0_711
	s_waitcnt lgkmcnt(0)
	v_cvt_pk_bf16_f32 v3, v3, v4
	v_add_co_u32_e32 v4, vcc, 0x10000, v82
	s_nop 1
	v_addc_co_u32_e32 v5, vcc, 0, v83, vcc
	global_store_dword v[4:5], v3, off offset:2048
.LBB0_711:
	s_or_b64 exec, exec, s[18:19]
	v_mul_f32_e32 v3, v41, v2
	s_waitcnt lgkmcnt(0)
	s_nop 1
	v_mov_b32_dpp v4, v3 quad_perm:[1,0,3,2] row_mask:0xf bank_mask:0xf
	s_and_saveexec_b64 s[18:19], s[0:1]
	s_cbranch_execz .LBB0_713
	s_waitcnt lgkmcnt(0)
	v_cvt_pk_bf16_f32 v3, v3, v4
	v_add_co_u32_e32 v4, vcc, 0x10000, v82
	s_nop 1
	v_addc_co_u32_e32 v5, vcc, 0, v83, vcc
	global_store_dword v[4:5], v3, off offset:2112
.LBB0_713:
	s_or_b64 exec, exec, s[18:19]
	v_mul_f32_e32 v3, v25, v2
	s_waitcnt lgkmcnt(0)
	s_nop 1
	v_mov_b32_dpp v4, v3 quad_perm:[1,0,3,2] row_mask:0xf bank_mask:0xf
	s_and_saveexec_b64 s[18:19], s[0:1]
	s_cbranch_execz .LBB0_715
	s_waitcnt lgkmcnt(0)
	v_cvt_pk_bf16_f32 v3, v3, v4
	v_add_co_u32_e32 v4, vcc, 0x10000, v82
	s_nop 1
	v_addc_co_u32_e32 v5, vcc, 0, v83, vcc
	global_store_dword v[4:5], v3, off offset:2176
.LBB0_715:
	s_or_b64 exec, exec, s[18:19]
	v_mul_f32_e32 v2, v9, v2
	s_nop 1
	v_mov_b32_dpp v3, v2 quad_perm:[1,0,3,2] row_mask:0xf bank_mask:0xf
	s_and_saveexec_b64 s[18:19], s[0:1]
	s_cbranch_execz .LBB0_717
	s_waitcnt lgkmcnt(0)
	v_cvt_pk_bf16_f32 v4, v2, v3
	v_add_co_u32_e32 v2, vcc, 0x10000, v82
	s_nop 1
	v_addc_co_u32_e32 v3, vcc, 0, v83, vcc
	global_store_dword v[2:3], v4, off offset:2240
.LBB0_717:
	s_or_b64 exec, exec, s[18:19]
	v_rcp_f32_e32 v2, v70
	s_waitcnt lgkmcnt(0)
	v_mul_f32_e32 v3, v58, v2
	s_nop 1
	v_mov_b32_dpp v4, v3 quad_perm:[1,0,3,2] row_mask:0xf bank_mask:0xf
	s_and_saveexec_b64 s[18:19], s[0:1]
	s_cbranch_execz .LBB0_719
	s_waitcnt lgkmcnt(0)
	v_cvt_pk_bf16_f32 v3, v3, v4
	v_add_co_u32_e32 v4, vcc, 0x18000, v82
	s_nop 1
	v_addc_co_u32_e32 v5, vcc, 0, v83, vcc
	global_store_dword v[4:5], v3, off
.LBB0_719:
	s_or_b64 exec, exec, s[18:19]
	v_mul_f32_e32 v3, v42, v2
	s_waitcnt lgkmcnt(0)
	s_nop 1
	v_mov_b32_dpp v4, v3 quad_perm:[1,0,3,2] row_mask:0xf bank_mask:0xf
	s_and_saveexec_b64 s[18:19], s[0:1]
	s_cbranch_execz .LBB0_721
	s_waitcnt lgkmcnt(0)
	v_cvt_pk_bf16_f32 v3, v3, v4
	v_add_co_u32_e32 v4, vcc, 0x18000, v82
	s_nop 1
	v_addc_co_u32_e32 v5, vcc, 0, v83, vcc
	global_store_dword v[4:5], v3, off offset:64
.LBB0_721:
	s_or_b64 exec, exec, s[18:19]
	v_mul_f32_e32 v3, v26, v2
	s_waitcnt lgkmcnt(0)
	s_nop 1
	v_mov_b32_dpp v4, v3 quad_perm:[1,0,3,2] row_mask:0xf bank_mask:0xf
	s_and_saveexec_b64 s[18:19], s[0:1]
	s_cbranch_execz .LBB0_723
	s_waitcnt lgkmcnt(0)
	v_cvt_pk_bf16_f32 v3, v3, v4
	v_add_co_u32_e32 v4, vcc, 0x18000, v82
	s_nop 1
	v_addc_co_u32_e32 v5, vcc, 0, v83, vcc
	global_store_dword v[4:5], v3, off offset:128
.LBB0_723:
	s_or_b64 exec, exec, s[18:19]
	v_mul_f32_e32 v2, v10, v2
	s_nop 1
	v_mov_b32_dpp v3, v2 quad_perm:[1,0,3,2] row_mask:0xf bank_mask:0xf
	s_and_saveexec_b64 s[18:19], s[0:1]
	s_cbranch_execz .LBB0_725
	s_waitcnt lgkmcnt(0)
	v_cvt_pk_bf16_f32 v4, v2, v3
	v_add_co_u32_e32 v2, vcc, 0x18000, v82
	s_nop 1
	v_addc_co_u32_e32 v3, vcc, 0, v83, vcc
	global_store_dword v[2:3], v4, off offset:192
.LBB0_725:
	s_or_b64 exec, exec, s[18:19]
	v_rcp_f32_e32 v2, v71
	s_waitcnt lgkmcnt(0)
	v_mul_f32_e32 v3, v59, v2
	s_nop 1
	v_mov_b32_dpp v4, v3 quad_perm:[1,0,3,2] row_mask:0xf bank_mask:0xf
	s_and_saveexec_b64 s[18:19], s[0:1]
	s_cbranch_execz .LBB0_727
	s_waitcnt lgkmcnt(0)
	v_cvt_pk_bf16_f32 v3, v3, v4
	v_add_co_u32_e32 v4, vcc, 0x19000, v82
	s_nop 1
	v_addc_co_u32_e32 v5, vcc, 0, v83, vcc
	global_store_dword v[4:5], v3, off offset:2048
.LBB0_727:
	s_or_b64 exec, exec, s[18:19]
	v_mul_f32_e32 v3, v43, v2
	s_waitcnt lgkmcnt(0)
	s_nop 1
	v_mov_b32_dpp v4, v3 quad_perm:[1,0,3,2] row_mask:0xf bank_mask:0xf
	s_and_saveexec_b64 s[18:19], s[0:1]
	s_cbranch_execz .LBB0_729
	s_waitcnt lgkmcnt(0)
	v_cvt_pk_bf16_f32 v3, v3, v4
	v_add_co_u32_e32 v4, vcc, 0x19000, v82
	s_nop 1
	v_addc_co_u32_e32 v5, vcc, 0, v83, vcc
	global_store_dword v[4:5], v3, off offset:2112
.LBB0_729:
	s_or_b64 exec, exec, s[18:19]
	v_mul_f32_e32 v3, v27, v2
	s_waitcnt lgkmcnt(0)
	s_nop 1
	v_mov_b32_dpp v4, v3 quad_perm:[1,0,3,2] row_mask:0xf bank_mask:0xf
	s_and_saveexec_b64 s[18:19], s[0:1]
	s_cbranch_execz .LBB0_731
	s_waitcnt lgkmcnt(0)
	v_cvt_pk_bf16_f32 v3, v3, v4
	v_add_co_u32_e32 v4, vcc, 0x19000, v82
	s_nop 1
	v_addc_co_u32_e32 v5, vcc, 0, v83, vcc
	global_store_dword v[4:5], v3, off offset:2176
.LBB0_731:
	s_or_b64 exec, exec, s[18:19]
	v_mul_f32_e32 v2, v11, v2
	s_nop 1
	v_mov_b32_dpp v3, v2 quad_perm:[1,0,3,2] row_mask:0xf bank_mask:0xf
	s_and_saveexec_b64 s[18:19], s[0:1]
	s_cbranch_execz .LBB0_733
	s_waitcnt lgkmcnt(0)
	v_cvt_pk_bf16_f32 v4, v2, v3
	v_add_co_u32_e32 v2, vcc, 0x19000, v82
	s_nop 1
	v_addc_co_u32_e32 v3, vcc, 0, v83, vcc
	global_store_dword v[2:3], v4, off offset:2240
.LBB0_733:
	s_or_b64 exec, exec, s[18:19]
	v_rcp_f32_e32 v2, v72
	s_waitcnt lgkmcnt(0)
	v_mul_f32_e32 v3, v60, v2
	s_nop 1
	v_mov_b32_dpp v4, v3 quad_perm:[1,0,3,2] row_mask:0xf bank_mask:0xf
	s_and_saveexec_b64 s[18:19], s[0:1]
	s_cbranch_execz .LBB0_735
	s_waitcnt lgkmcnt(0)
	v_cvt_pk_bf16_f32 v3, v3, v4
	v_add_co_u32_e32 v4, vcc, 0x1b000, v82
	s_nop 1
	v_addc_co_u32_e32 v5, vcc, 0, v83, vcc
	global_store_dword v[4:5], v3, off
.LBB0_735:
	s_or_b64 exec, exec, s[18:19]
	v_mul_f32_e32 v3, v44, v2
	s_waitcnt lgkmcnt(0)
	s_nop 1
	v_mov_b32_dpp v4, v3 quad_perm:[1,0,3,2] row_mask:0xf bank_mask:0xf
	s_and_saveexec_b64 s[18:19], s[0:1]
	s_cbranch_execz .LBB0_737
	s_waitcnt lgkmcnt(0)
	v_cvt_pk_bf16_f32 v3, v3, v4
	v_add_co_u32_e32 v4, vcc, 0x1b000, v82
	s_nop 1
	v_addc_co_u32_e32 v5, vcc, 0, v83, vcc
	global_store_dword v[4:5], v3, off offset:64
.LBB0_737:
	s_or_b64 exec, exec, s[18:19]
	v_mul_f32_e32 v3, v28, v2
	s_waitcnt lgkmcnt(0)
	s_nop 1
	v_mov_b32_dpp v4, v3 quad_perm:[1,0,3,2] row_mask:0xf bank_mask:0xf
	s_and_saveexec_b64 s[18:19], s[0:1]
	s_cbranch_execz .LBB0_739
	s_waitcnt lgkmcnt(0)
	v_cvt_pk_bf16_f32 v3, v3, v4
	v_add_co_u32_e32 v4, vcc, 0x1b000, v82
	s_nop 1
	v_addc_co_u32_e32 v5, vcc, 0, v83, vcc
	global_store_dword v[4:5], v3, off offset:128
.LBB0_739:
	s_or_b64 exec, exec, s[18:19]
	v_mul_f32_e32 v2, v12, v2
	s_nop 1
	v_mov_b32_dpp v3, v2 quad_perm:[1,0,3,2] row_mask:0xf bank_mask:0xf
	s_and_saveexec_b64 s[18:19], s[0:1]
	s_cbranch_execz .LBB0_741
	s_waitcnt lgkmcnt(0)
	v_cvt_pk_bf16_f32 v4, v2, v3
	v_add_co_u32_e32 v2, vcc, 0x1b000, v82
	s_nop 1
	v_addc_co_u32_e32 v3, vcc, 0, v83, vcc
	global_store_dword v[2:3], v4, off offset:192
.LBB0_741:
	s_or_b64 exec, exec, s[18:19]
	v_rcp_f32_e32 v2, v73
	s_waitcnt lgkmcnt(0)
	v_mul_f32_e32 v3, v61, v2
	s_nop 1
	v_mov_b32_dpp v4, v3 quad_perm:[1,0,3,2] row_mask:0xf bank_mask:0xf
	s_and_saveexec_b64 s[18:19], s[0:1]
	s_cbranch_execz .LBB0_743
	s_waitcnt lgkmcnt(0)
	v_cvt_pk_bf16_f32 v3, v3, v4
	v_add_co_u32_e32 v4, vcc, 0x1c000, v82
	s_nop 1
	v_addc_co_u32_e32 v5, vcc, 0, v83, vcc
	global_store_dword v[4:5], v3, off offset:2048
.LBB0_743:
	s_or_b64 exec, exec, s[18:19]
	v_mul_f32_e32 v3, v45, v2
	s_waitcnt lgkmcnt(0)
	s_nop 1
	v_mov_b32_dpp v4, v3 quad_perm:[1,0,3,2] row_mask:0xf bank_mask:0xf
	s_and_saveexec_b64 s[18:19], s[0:1]
	s_cbranch_execz .LBB0_745
	s_waitcnt lgkmcnt(0)
	v_cvt_pk_bf16_f32 v3, v3, v4
	v_add_co_u32_e32 v4, vcc, 0x1c000, v82
	s_nop 1
	v_addc_co_u32_e32 v5, vcc, 0, v83, vcc
	global_store_dword v[4:5], v3, off offset:2112
.LBB0_745:
	s_or_b64 exec, exec, s[18:19]
	v_mul_f32_e32 v3, v29, v2
	s_waitcnt lgkmcnt(0)
	s_nop 1
	v_mov_b32_dpp v4, v3 quad_perm:[1,0,3,2] row_mask:0xf bank_mask:0xf
	s_and_saveexec_b64 s[18:19], s[0:1]
	s_cbranch_execz .LBB0_747
	s_waitcnt lgkmcnt(0)
	v_cvt_pk_bf16_f32 v3, v3, v4
	v_add_co_u32_e32 v4, vcc, 0x1c000, v82
	s_nop 1
	v_addc_co_u32_e32 v5, vcc, 0, v83, vcc
	global_store_dword v[4:5], v3, off offset:2176
.LBB0_747:
	s_or_b64 exec, exec, s[18:19]
	v_mul_f32_e32 v2, v13, v2
	s_nop 1
	v_mov_b32_dpp v3, v2 quad_perm:[1,0,3,2] row_mask:0xf bank_mask:0xf
	s_and_saveexec_b64 s[18:19], s[0:1]
	s_cbranch_execz .LBB0_749
	s_waitcnt lgkmcnt(0)
	v_cvt_pk_bf16_f32 v4, v2, v3
	v_add_co_u32_e32 v2, vcc, 0x1c000, v82
	s_nop 1
	v_addc_co_u32_e32 v3, vcc, 0, v83, vcc
	global_store_dword v[2:3], v4, off offset:2240
.LBB0_749:
	s_or_b64 exec, exec, s[18:19]
	v_rcp_f32_e32 v2, v66
	s_waitcnt lgkmcnt(0)
	v_mul_f32_e32 v3, v62, v2
	s_nop 1
	v_mov_b32_dpp v4, v3 quad_perm:[1,0,3,2] row_mask:0xf bank_mask:0xf
	s_and_saveexec_b64 s[18:19], s[0:1]
	s_cbranch_execz .LBB0_751
	s_waitcnt lgkmcnt(0)
	v_cvt_pk_bf16_f32 v3, v3, v4
	v_add_co_u32_e32 v4, vcc, 0x24000, v82
	s_nop 1
	v_addc_co_u32_e32 v5, vcc, 0, v83, vcc
	global_store_dword v[4:5], v3, off
.LBB0_751:
	s_or_b64 exec, exec, s[18:19]
	v_mul_f32_e32 v3, v46, v2
	s_waitcnt lgkmcnt(0)
	s_nop 1
	v_mov_b32_dpp v4, v3 quad_perm:[1,0,3,2] row_mask:0xf bank_mask:0xf
	s_and_saveexec_b64 s[18:19], s[0:1]
	s_cbranch_execz .LBB0_753
	s_waitcnt lgkmcnt(0)
	v_cvt_pk_bf16_f32 v3, v3, v4
	v_add_co_u32_e32 v4, vcc, 0x24000, v82
	s_nop 1
	v_addc_co_u32_e32 v5, vcc, 0, v83, vcc
	global_store_dword v[4:5], v3, off offset:64
.LBB0_753:
	s_or_b64 exec, exec, s[18:19]
	v_mul_f32_e32 v3, v30, v2
	s_waitcnt lgkmcnt(0)
	s_nop 1
	v_mov_b32_dpp v4, v3 quad_perm:[1,0,3,2] row_mask:0xf bank_mask:0xf
	s_and_saveexec_b64 s[18:19], s[0:1]
	s_cbranch_execz .LBB0_755
	s_waitcnt lgkmcnt(0)
	v_cvt_pk_bf16_f32 v3, v3, v4
	v_add_co_u32_e32 v4, vcc, 0x24000, v82
	s_nop 1
	v_addc_co_u32_e32 v5, vcc, 0, v83, vcc
	global_store_dword v[4:5], v3, off offset:128
.LBB0_755:
	s_or_b64 exec, exec, s[18:19]
	v_mul_f32_e32 v2, v14, v2
	s_nop 1
	v_mov_b32_dpp v3, v2 quad_perm:[1,0,3,2] row_mask:0xf bank_mask:0xf
	s_and_saveexec_b64 s[18:19], s[0:1]
	s_cbranch_execz .LBB0_757
	s_waitcnt lgkmcnt(0)
	v_cvt_pk_bf16_f32 v4, v2, v3
	v_add_co_u32_e32 v2, vcc, 0x24000, v82
	s_nop 1
	v_addc_co_u32_e32 v3, vcc, 0, v83, vcc
	global_store_dword v[2:3], v4, off offset:192
.LBB0_757:
	s_or_b64 exec, exec, s[18:19]
	v_rcp_f32_e32 v2, v67
	s_waitcnt lgkmcnt(0)
	v_mul_f32_e32 v3, v63, v2
	s_nop 1
	v_mov_b32_dpp v4, v3 quad_perm:[1,0,3,2] row_mask:0xf bank_mask:0xf
	s_and_saveexec_b64 s[18:19], s[0:1]
	s_cbranch_execz .LBB0_759
	s_waitcnt lgkmcnt(0)
	v_cvt_pk_bf16_f32 v3, v3, v4
	v_add_co_u32_e32 v4, vcc, 0x25000, v82
	s_nop 1
	v_addc_co_u32_e32 v5, vcc, 0, v83, vcc
	global_store_dword v[4:5], v3, off offset:2048
.LBB0_759:
	s_or_b64 exec, exec, s[18:19]
	v_mul_f32_e32 v3, v47, v2
	s_waitcnt lgkmcnt(0)
	s_nop 1
	v_mov_b32_dpp v4, v3 quad_perm:[1,0,3,2] row_mask:0xf bank_mask:0xf
	s_and_saveexec_b64 s[18:19], s[0:1]
	s_cbranch_execz .LBB0_761
	s_waitcnt lgkmcnt(0)
	v_cvt_pk_bf16_f32 v3, v3, v4
	v_add_co_u32_e32 v4, vcc, 0x25000, v82
	s_nop 1
	v_addc_co_u32_e32 v5, vcc, 0, v83, vcc
	global_store_dword v[4:5], v3, off offset:2112
.LBB0_761:
	s_or_b64 exec, exec, s[18:19]
	v_mul_f32_e32 v3, v31, v2
	s_waitcnt lgkmcnt(0)
	s_nop 1
	v_mov_b32_dpp v4, v3 quad_perm:[1,0,3,2] row_mask:0xf bank_mask:0xf
	s_and_saveexec_b64 s[18:19], s[0:1]
	s_cbranch_execz .LBB0_763
	s_waitcnt lgkmcnt(0)
	v_cvt_pk_bf16_f32 v3, v3, v4
	v_add_co_u32_e32 v4, vcc, 0x25000, v82
	s_nop 1
	v_addc_co_u32_e32 v5, vcc, 0, v83, vcc
	global_store_dword v[4:5], v3, off offset:2176
.LBB0_763:
	s_or_b64 exec, exec, s[18:19]
	v_mul_f32_e32 v2, v15, v2
	s_nop 1
	v_mov_b32_dpp v3, v2 quad_perm:[1,0,3,2] row_mask:0xf bank_mask:0xf
	s_and_saveexec_b64 s[18:19], s[0:1]
	s_cbranch_execz .LBB0_765
	s_waitcnt lgkmcnt(0)
	v_cvt_pk_bf16_f32 v4, v2, v3
	v_add_co_u32_e32 v2, vcc, 0x25000, v82
	s_nop 1
	v_addc_co_u32_e32 v3, vcc, 0, v83, vcc
	global_store_dword v[2:3], v4, off offset:2240
.LBB0_765:
	s_or_b64 exec, exec, s[18:19]
	v_rcp_f32_e32 v2, v68
	s_waitcnt lgkmcnt(0)
	v_mul_f32_e32 v3, v64, v2
	s_nop 1
	v_mov_b32_dpp v4, v3 quad_perm:[1,0,3,2] row_mask:0xf bank_mask:0xf
	s_and_saveexec_b64 s[18:19], s[0:1]
	s_cbranch_execz .LBB0_767
	s_waitcnt lgkmcnt(0)
	v_cvt_pk_bf16_f32 v3, v3, v4
	v_add_co_u32_e32 v4, vcc, 0x27000, v82
	s_nop 1
	v_addc_co_u32_e32 v5, vcc, 0, v83, vcc
	global_store_dword v[4:5], v3, off
.LBB0_767:
	s_or_b64 exec, exec, s[18:19]
	v_mul_f32_e32 v3, v48, v2
	s_waitcnt lgkmcnt(0)
	s_nop 1
	v_mov_b32_dpp v4, v3 quad_perm:[1,0,3,2] row_mask:0xf bank_mask:0xf
	s_and_saveexec_b64 s[18:19], s[0:1]
	s_cbranch_execz .LBB0_769
	s_waitcnt lgkmcnt(0)
	v_cvt_pk_bf16_f32 v3, v3, v4
	v_add_co_u32_e32 v4, vcc, 0x27000, v82
	s_nop 1
	v_addc_co_u32_e32 v5, vcc, 0, v83, vcc
	global_store_dword v[4:5], v3, off offset:64
.LBB0_769:
	s_or_b64 exec, exec, s[18:19]
	v_mul_f32_e32 v3, v32, v2
	s_waitcnt lgkmcnt(0)
	s_nop 1
	v_mov_b32_dpp v4, v3 quad_perm:[1,0,3,2] row_mask:0xf bank_mask:0xf
	s_and_saveexec_b64 s[18:19], s[0:1]
	s_cbranch_execz .LBB0_771
	s_waitcnt lgkmcnt(0)
	v_cvt_pk_bf16_f32 v3, v3, v4
	v_add_co_u32_e32 v4, vcc, 0x27000, v82
	s_nop 1
	v_addc_co_u32_e32 v5, vcc, 0, v83, vcc
	global_store_dword v[4:5], v3, off offset:128
.LBB0_771:
	s_or_b64 exec, exec, s[18:19]
	v_mul_f32_e32 v2, v16, v2
	s_nop 1
	v_mov_b32_dpp v3, v2 quad_perm:[1,0,3,2] row_mask:0xf bank_mask:0xf
	s_and_saveexec_b64 s[18:19], s[0:1]
	s_cbranch_execz .LBB0_773
	s_waitcnt lgkmcnt(0)
	v_cvt_pk_bf16_f32 v4, v2, v3
	v_add_co_u32_e32 v2, vcc, 0x27000, v82
	s_nop 1
	v_addc_co_u32_e32 v3, vcc, 0, v83, vcc
	global_store_dword v[2:3], v4, off offset:192
.LBB0_773:
	s_or_b64 exec, exec, s[18:19]
	v_rcp_f32_e32 v2, v69
	s_waitcnt lgkmcnt(0)
	v_mul_f32_e32 v3, v65, v2
	s_nop 1
	v_mov_b32_dpp v4, v3 quad_perm:[1,0,3,2] row_mask:0xf bank_mask:0xf
	s_and_saveexec_b64 s[18:19], s[0:1]
	s_cbranch_execz .LBB0_775
	s_waitcnt lgkmcnt(0)
	v_cvt_pk_bf16_f32 v3, v3, v4
	v_add_co_u32_e32 v4, vcc, 0x28000, v82
	s_nop 1
	v_addc_co_u32_e32 v5, vcc, 0, v83, vcc
	global_store_dword v[4:5], v3, off offset:2048
.LBB0_775:
	s_or_b64 exec, exec, s[18:19]
	v_mul_f32_e32 v3, v49, v2
	s_waitcnt lgkmcnt(0)
	s_nop 1
	v_mov_b32_dpp v4, v3 quad_perm:[1,0,3,2] row_mask:0xf bank_mask:0xf
	s_and_saveexec_b64 s[18:19], s[0:1]
	s_cbranch_execz .LBB0_777
	s_waitcnt lgkmcnt(0)
	v_cvt_pk_bf16_f32 v3, v3, v4
	v_add_co_u32_e32 v4, vcc, 0x28000, v82
	s_nop 1
	v_addc_co_u32_e32 v5, vcc, 0, v83, vcc
	global_store_dword v[4:5], v3, off offset:2112
.LBB0_777:
	s_or_b64 exec, exec, s[18:19]
	v_mul_f32_e32 v3, v33, v2
	s_waitcnt lgkmcnt(0)
	s_nop 1
	v_mov_b32_dpp v4, v3 quad_perm:[1,0,3,2] row_mask:0xf bank_mask:0xf
	s_and_saveexec_b64 s[18:19], s[0:1]
	s_cbranch_execz .LBB0_779
	s_waitcnt lgkmcnt(0)
	v_cvt_pk_bf16_f32 v3, v3, v4
	v_add_co_u32_e32 v4, vcc, 0x28000, v82
	s_nop 1
	v_addc_co_u32_e32 v5, vcc, 0, v83, vcc
	global_store_dword v[4:5], v3, off offset:2176
.LBB0_779:
	s_or_b64 exec, exec, s[18:19]
	v_mul_f32_e32 v2, v17, v2
	s_nop 1
	v_mov_b32_dpp v3, v2 quad_perm:[1,0,3,2] row_mask:0xf bank_mask:0xf
	s_and_saveexec_b64 s[18:19], s[0:1]
	s_cbranch_execz .LBB0_781
	s_waitcnt lgkmcnt(0)
	v_cvt_pk_bf16_f32 v4, v2, v3
	v_add_co_u32_e32 v2, vcc, 0x28000, v82
	s_nop 1
	v_addc_co_u32_e32 v3, vcc, 0, v83, vcc
	global_store_dword v[2:3], v4, off offset:2240

.LBB0_820:
	s_or_b64 exec, exec, s[4:5]
	ds_read_b128 v[78:81], v184
	ds_read_b128 v[74:77], v184 offset:32
	s_mul_hi_i32 s0, s19, 0x1800
	s_mulk_i32 s19, 0x1800
	s_add_u32 s1, s58, s19
	s_waitcnt lgkmcnt(1)
	v_rcp_f32_e32 v78, v78
	s_addc_u32 s0, s59, s0
	s_lshl_b32 s60, s18, 1
	s_add_u32 s1, s1, s60
	s_addc_u32 s0, s0, 0
	s_mul_hi_i32 s5, s70, 0x6000
	s_mulk_i32 s70, 0x6000
	v_mul_f32_e32 v50, v50, v78
	ds_read_b128 v[70:73], v184 offset:64
	ds_read_b128 v[66:69], v184 offset:96
	s_add_u32 s4, s1, s70
	s_nop 1
	v_mov_b32_dpp v86, v50 quad_perm:[1,0,3,2] row_mask:0xf bank_mask:0xf
	s_addc_u32 s5, s0, s5
	v_and_b32_e32 v82, 1, v179
	v_lshlrev_b32_e32 v162, 1, v181
	v_cmp_eq_u32_e64 s[0:1], 0, v82
	v_lshl_add_u64 v[82:83], s[4:5], 0, v[162:163]
	v_mul_u32_u24_e32 v162, 0x18000, v180
	v_lshl_add_u64 v[84:85], v[82:83], 0, v[162:163]
	v_lshl_add_u64 v[82:83], v[84:85], 0, s[10:11]
	s_and_saveexec_b64 s[4:5], s[0:1]
	s_cbranch_execz .LBB0_822
	s_waitcnt lgkmcnt(0)
	v_cvt_pk_bf16_f32 v50, v50, v86
	global_store_dword v[82:83], v50, off
.LBB0_822:
	s_or_b64 exec, exec, s[4:5]
	v_mul_f32_e32 v34, v34, v78
	s_nop 1
	v_mov_b32_dpp v50, v34 quad_perm:[1,0,3,2] row_mask:0xf bank_mask:0xf
	s_and_saveexec_b64 s[4:5], s[0:1]
	s_cbranch_execz .LBB0_824
	s_waitcnt lgkmcnt(0)
	v_cvt_pk_bf16_f32 v34, v34, v50
	global_store_dword v[84:85], v34, off offset:2112
.LBB0_824:
	s_or_b64 exec, exec, s[4:5]
	v_mul_f32_e32 v18, v18, v78
	s_nop 1
	v_mov_b32_dpp v34, v18 quad_perm:[1,0,3,2] row_mask:0xf bank_mask:0xf
	s_and_saveexec_b64 s[4:5], s[0:1]
	s_cbranch_execz .LBB0_826
	s_waitcnt lgkmcnt(0)
	v_cvt_pk_bf16_f32 v18, v18, v34
	global_store_dword v[84:85], v18, off offset:2176
.LBB0_826:
	s_or_b64 exec, exec, s[4:5]
	v_mul_f32_e32 v2, v2, v78
	s_nop 1
	v_mov_b32_dpp v18, v2 quad_perm:[1,0,3,2] row_mask:0xf bank_mask:0xf
	s_and_saveexec_b64 s[4:5], s[0:1]
	s_cbranch_execz .LBB0_828
	s_waitcnt lgkmcnt(0)
	v_cvt_pk_bf16_f32 v2, v2, v18
	global_store_dword v[84:85], v2, off offset:2240
.LBB0_828:
	s_or_b64 exec, exec, s[4:5]
	v_rcp_f32_e32 v2, v79
	s_waitcnt lgkmcnt(0)
	v_mul_f32_e32 v18, v51, v2
	s_nop 1
	v_mov_b32_dpp v34, v18 quad_perm:[1,0,3,2] row_mask:0xf bank_mask:0xf
	s_and_saveexec_b64 s[4:5], s[0:1]
	s_cbranch_execz .LBB0_830
	v_add_co_u32_e32 v50, vcc, 0x6000, v82
	s_waitcnt lgkmcnt(0)
	v_cvt_pk_bf16_f32 v18, v18, v34
	s_nop 0
	v_addc_co_u32_e32 v51, vcc, 0, v83, vcc
	global_store_dword v[50:51], v18, off
.LBB0_830:
	s_or_b64 exec, exec, s[4:5]
	v_mul_f32_e32 v18, v35, v2
	s_waitcnt lgkmcnt(0)
	s_nop 1
	v_mov_b32_dpp v34, v18 quad_perm:[1,0,3,2] row_mask:0xf bank_mask:0xf
	s_and_saveexec_b64 s[4:5], s[0:1]
	s_cbranch_execz .LBB0_832
	s_waitcnt lgkmcnt(0)
	v_cvt_pk_bf16_f32 v18, v18, v34
	v_add_co_u32_e32 v34, vcc, 0x6000, v82
	s_nop 1
	v_addc_co_u32_e32 v35, vcc, 0, v83, vcc
	global_store_dword v[34:35], v18, off offset:64
.LBB0_832:
	s_or_b64 exec, exec, s[4:5]
	v_mul_f32_e32 v18, v19, v2
	s_nop 1
	v_mov_b32_dpp v19, v18 quad_perm:[1,0,3,2] row_mask:0xf bank_mask:0xf
	s_and_saveexec_b64 s[4:5], s[0:1]
	s_cbranch_execz .LBB0_834
	s_waitcnt lgkmcnt(0)
	v_cvt_pk_bf16_f32 v34, v18, v19
	v_add_co_u32_e32 v18, vcc, 0x6000, v82
	s_nop 1
	v_addc_co_u32_e32 v19, vcc, 0, v83, vcc
	global_store_dword v[18:19], v34, off offset:128
.LBB0_834:
	s_or_b64 exec, exec, s[4:5]
	v_mul_f32_e32 v2, v3, v2
	s_nop 1
	v_mov_b32_dpp v3, v2 quad_perm:[1,0,3,2] row_mask:0xf bank_mask:0xf
	s_and_saveexec_b64 s[4:5], s[0:1]
	s_cbranch_execz .LBB0_836
	s_waitcnt lgkmcnt(0)
	v_cvt_pk_bf16_f32 v18, v2, v3
	v_add_co_u32_e32 v2, vcc, 0x6000, v82
	s_nop 1
	v_addc_co_u32_e32 v3, vcc, 0, v83, vcc
	global_store_dword v[2:3], v18, off offset:192
.LBB0_836:
	s_or_b64 exec, exec, s[4:5]
	v_rcp_f32_e32 v2, v80
	s_waitcnt lgkmcnt(0)
	v_mul_f32_e32 v3, v52, v2
	s_nop 1
	v_mov_b32_dpp v18, v3 quad_perm:[1,0,3,2] row_mask:0xf bank_mask:0xf
	s_and_saveexec_b64 s[4:5], s[0:1]
	s_cbranch_execz .LBB0_838
	s_waitcnt lgkmcnt(0)
	v_cvt_pk_bf16_f32 v3, v3, v18
	v_add_co_u32_e32 v18, vcc, 0xc000, v82
	s_nop 1
	v_addc_co_u32_e32 v19, vcc, 0, v83, vcc
	global_store_dword v[18:19], v3, off
.LBB0_838:
	s_or_b64 exec, exec, s[4:5]
	v_mul_f32_e32 v3, v36, v2
	s_waitcnt lgkmcnt(0)
	s_nop 1
	v_mov_b32_dpp v18, v3 quad_perm:[1,0,3,2] row_mask:0xf bank_mask:0xf
	s_and_saveexec_b64 s[4:5], s[0:1]
	s_cbranch_execz .LBB0_840
	s_waitcnt lgkmcnt(0)
	v_cvt_pk_bf16_f32 v3, v3, v18
	v_add_co_u32_e32 v18, vcc, 0xc000, v82
	s_nop 1
	v_addc_co_u32_e32 v19, vcc, 0, v83, vcc
	global_store_dword v[18:19], v3, off offset:64
.LBB0_840:
	s_or_b64 exec, exec, s[4:5]
	v_mul_f32_e32 v3, v20, v2
	s_waitcnt lgkmcnt(0)
	s_nop 1
	v_mov_b32_dpp v18, v3 quad_perm:[1,0,3,2] row_mask:0xf bank_mask:0xf
	s_and_saveexec_b64 s[4:5], s[0:1]
	s_cbranch_execz .LBB0_842
	s_waitcnt lgkmcnt(0)
	v_cvt_pk_bf16_f32 v3, v3, v18
	v_add_co_u32_e32 v18, vcc, 0xc000, v82
	s_nop 1
	v_addc_co_u32_e32 v19, vcc, 0, v83, vcc
	global_store_dword v[18:19], v3, off offset:128
.LBB0_842:
	s_or_b64 exec, exec, s[4:5]
	v_mul_f32_e32 v2, v4, v2
	s_nop 1
	v_mov_b32_dpp v3, v2 quad_perm:[1,0,3,2] row_mask:0xf bank_mask:0xf
	s_and_saveexec_b64 s[4:5], s[0:1]
	s_cbranch_execz .LBB0_844
	s_waitcnt lgkmcnt(0)
	v_cvt_pk_bf16_f32 v4, v2, v3
	v_add_co_u32_e32 v2, vcc, 0xc000, v82
	s_nop 1
	v_addc_co_u32_e32 v3, vcc, 0, v83, vcc
	global_store_dword v[2:3], v4, off offset:192
.LBB0_844:
	s_or_b64 exec, exec, s[4:5]
	v_rcp_f32_e32 v2, v81
	s_waitcnt lgkmcnt(0)
	v_mul_f32_e32 v3, v53, v2
	s_nop 1
	v_mov_b32_dpp v4, v3 quad_perm:[1,0,3,2] row_mask:0xf bank_mask:0xf
	s_and_saveexec_b64 s[4:5], s[0:1]
	s_cbranch_execz .LBB0_846
	v_add_co_u32_e32 v18, vcc, 0x12000, v82
	s_waitcnt lgkmcnt(0)
	v_cvt_pk_bf16_f32 v3, v3, v4
	s_nop 0
	v_addc_co_u32_e32 v19, vcc, 0, v83, vcc
	global_store_dword v[18:19], v3, off
.LBB0_846:
	s_or_b64 exec, exec, s[4:5]
	v_mul_f32_e32 v3, v37, v2
	s_waitcnt lgkmcnt(0)
	s_nop 1
	v_mov_b32_dpp v4, v3 quad_perm:[1,0,3,2] row_mask:0xf bank_mask:0xf
	s_and_saveexec_b64 s[4:5], s[0:1]
	s_cbranch_execz .LBB0_848
	v_add_co_u32_e32 v18, vcc, 0x12000, v82
	s_waitcnt lgkmcnt(0)
	v_cvt_pk_bf16_f32 v3, v3, v4
	s_nop 0
	v_addc_co_u32_e32 v19, vcc, 0, v83, vcc
	global_store_dword v[18:19], v3, off offset:64
.LBB0_848:
	s_or_b64 exec, exec, s[4:5]
	v_mul_f32_e32 v3, v21, v2
	s_waitcnt lgkmcnt(0)
	s_nop 1
	v_mov_b32_dpp v4, v3 quad_perm:[1,0,3,2] row_mask:0xf bank_mask:0xf
	s_and_saveexec_b64 s[4:5], s[0:1]
	s_cbranch_execz .LBB0_850
	v_add_co_u32_e32 v18, vcc, 0x12000, v82
	s_waitcnt lgkmcnt(0)
	v_cvt_pk_bf16_f32 v3, v3, v4
	s_nop 0
	v_addc_co_u32_e32 v19, vcc, 0, v83, vcc
	global_store_dword v[18:19], v3, off offset:128
.LBB0_850:
	s_or_b64 exec, exec, s[4:5]
	v_mul_f32_e32 v2, v5, v2
	s_nop 1
	v_mov_b32_dpp v3, v2 quad_perm:[1,0,3,2] row_mask:0xf bank_mask:0xf
	s_and_saveexec_b64 s[4:5], s[0:1]
	s_cbranch_execz .LBB0_852
	s_waitcnt lgkmcnt(0)
	v_cvt_pk_bf16_f32 v4, v2, v3
	v_add_co_u32_e32 v2, vcc, 0x12000, v82
	s_nop 1
	v_addc_co_u32_e32 v3, vcc, 0, v83, vcc
	global_store_dword v[2:3], v4, off offset:192
.LBB0_852:
	s_or_b64 exec, exec, s[4:5]
	v_rcp_f32_e32 v2, v74
	s_waitcnt lgkmcnt(0)
	v_mul_f32_e32 v3, v54, v2
	s_nop 1
	v_mov_b32_dpp v4, v3 quad_perm:[1,0,3,2] row_mask:0xf bank_mask:0xf
	s_and_saveexec_b64 s[4:5], s[0:1]
	s_cbranch_execz .LBB0_854
	s_waitcnt lgkmcnt(0)
	v_cvt_pk_bf16_f32 v3, v3, v4
	v_add_co_u32_e32 v4, vcc, 0x30000, v82
	s_nop 1
	v_addc_co_u32_e32 v5, vcc, 0, v83, vcc
	global_store_dword v[4:5], v3, off
.LBB0_854:
	s_or_b64 exec, exec, s[4:5]
	v_mul_f32_e32 v3, v38, v2
	s_waitcnt lgkmcnt(0)
	s_nop 1
	v_mov_b32_dpp v4, v3 quad_perm:[1,0,3,2] row_mask:0xf bank_mask:0xf
	s_and_saveexec_b64 s[4:5], s[0:1]
	s_cbranch_execz .LBB0_856
	s_waitcnt lgkmcnt(0)
	v_cvt_pk_bf16_f32 v3, v3, v4
	v_add_co_u32_e32 v4, vcc, 0x30000, v82
	s_nop 1
	v_addc_co_u32_e32 v5, vcc, 0, v83, vcc
	global_store_dword v[4:5], v3, off offset:64
.LBB0_856:
	s_or_b64 exec, exec, s[4:5]
	v_mul_f32_e32 v3, v22, v2
	s_waitcnt lgkmcnt(0)
	s_nop 1
	v_mov_b32_dpp v4, v3 quad_perm:[1,0,3,2] row_mask:0xf bank_mask:0xf
	s_and_saveexec_b64 s[4:5], s[0:1]
	s_cbranch_execz .LBB0_858
	s_waitcnt lgkmcnt(0)
	v_cvt_pk_bf16_f32 v3, v3, v4
	v_add_co_u32_e32 v4, vcc, 0x30000, v82
	s_nop 1
	v_addc_co_u32_e32 v5, vcc, 0, v83, vcc
	global_store_dword v[4:5], v3, off offset:128
.LBB0_858:
	s_or_b64 exec, exec, s[4:5]
	v_mul_f32_e32 v2, v6, v2
	s_nop 1
	v_mov_b32_dpp v3, v2 quad_perm:[1,0,3,2] row_mask:0xf bank_mask:0xf
	s_and_saveexec_b64 s[4:5], s[0:1]
	s_cbranch_execz .LBB0_860
	s_waitcnt lgkmcnt(0)
	v_cvt_pk_bf16_f32 v4, v2, v3
	v_add_co_u32_e32 v2, vcc, 0x30000, v82
	s_nop 1
	v_addc_co_u32_e32 v3, vcc, 0, v83, vcc
	global_store_dword v[2:3], v4, off offset:192
.LBB0_860:
	s_or_b64 exec, exec, s[4:5]
	v_rcp_f32_e32 v2, v75
	s_waitcnt lgkmcnt(0)
	v_mul_f32_e32 v3, v55, v2
	s_nop 1
	v_mov_b32_dpp v4, v3 quad_perm:[1,0,3,2] row_mask:0xf bank_mask:0xf
	s_and_saveexec_b64 s[4:5], s[0:1]
	s_cbranch_execz .LBB0_862
	s_waitcnt lgkmcnt(0)
	v_cvt_pk_bf16_f32 v3, v3, v4
	v_add_co_u32_e32 v4, vcc, 0x36000, v82
	s_nop 1
	v_addc_co_u32_e32 v5, vcc, 0, v83, vcc
	global_store_dword v[4:5], v3, off
.LBB0_862:
	s_or_b64 exec, exec, s[4:5]
	v_mul_f32_e32 v3, v39, v2
	s_waitcnt lgkmcnt(0)
	s_nop 1
	v_mov_b32_dpp v4, v3 quad_perm:[1,0,3,2] row_mask:0xf bank_mask:0xf
	s_and_saveexec_b64 s[4:5], s[0:1]
	s_cbranch_execz .LBB0_864
	s_waitcnt lgkmcnt(0)
	v_cvt_pk_bf16_f32 v3, v3, v4
	v_add_co_u32_e32 v4, vcc, 0x36000, v82
	s_nop 1
	v_addc_co_u32_e32 v5, vcc, 0, v83, vcc
	global_store_dword v[4:5], v3, off offset:64
.LBB0_864:
	s_or_b64 exec, exec, s[4:5]
	v_mul_f32_e32 v3, v23, v2
	s_waitcnt lgkmcnt(0)
	s_nop 1
	v_mov_b32_dpp v4, v3 quad_perm:[1,0,3,2] row_mask:0xf bank_mask:0xf
	s_and_saveexec_b64 s[4:5], s[0:1]
	s_cbranch_execz .LBB0_866
	s_waitcnt lgkmcnt(0)
	v_cvt_pk_bf16_f32 v3, v3, v4
	v_add_co_u32_e32 v4, vcc, 0x36000, v82
	s_nop 1
	v_addc_co_u32_e32 v5, vcc, 0, v83, vcc
	global_store_dword v[4:5], v3, off offset:128
.LBB0_866:
	s_or_b64 exec, exec, s[4:5]
	v_mul_f32_e32 v2, v7, v2
	s_nop 1
	v_mov_b32_dpp v3, v2 quad_perm:[1,0,3,2] row_mask:0xf bank_mask:0xf
	s_and_saveexec_b64 s[4:5], s[0:1]
	s_cbranch_execz .LBB0_868
	s_waitcnt lgkmcnt(0)
	v_cvt_pk_bf16_f32 v4, v2, v3
	v_add_co_u32_e32 v2, vcc, 0x36000, v82
	s_nop 1
	v_addc_co_u32_e32 v3, vcc, 0, v83, vcc
	global_store_dword v[2:3], v4, off offset:192
.LBB0_868:
	s_or_b64 exec, exec, s[4:5]
	v_rcp_f32_e32 v2, v76
	s_waitcnt lgkmcnt(0)
	v_mul_f32_e32 v3, v56, v2
	s_nop 1
	v_mov_b32_dpp v4, v3 quad_perm:[1,0,3,2] row_mask:0xf bank_mask:0xf
	s_and_saveexec_b64 s[4:5], s[0:1]
	s_cbranch_execz .LBB0_870
	s_waitcnt lgkmcnt(0)
	v_cvt_pk_bf16_f32 v3, v3, v4
	v_add_co_u32_e32 v4, vcc, 0x3c000, v82
	s_nop 1
	v_addc_co_u32_e32 v5, vcc, 0, v83, vcc
	global_store_dword v[4:5], v3, off
.LBB0_870:
	s_or_b64 exec, exec, s[4:5]
	v_mul_f32_e32 v3, v40, v2
	s_waitcnt lgkmcnt(0)
	s_nop 1
	v_mov_b32_dpp v4, v3 quad_perm:[1,0,3,2] row_mask:0xf bank_mask:0xf
	s_and_saveexec_b64 s[4:5], s[0:1]
	s_cbranch_execz .LBB0_872
	s_waitcnt lgkmcnt(0)
	v_cvt_pk_bf16_f32 v3, v3, v4
	v_add_co_u32_e32 v4, vcc, 0x3c000, v82
	s_nop 1
	v_addc_co_u32_e32 v5, vcc, 0, v83, vcc
	global_store_dword v[4:5], v3, off offset:64
.LBB0_872:
	s_or_b64 exec, exec, s[4:5]
	v_mul_f32_e32 v3, v24, v2
	s_waitcnt lgkmcnt(0)
	s_nop 1
	v_mov_b32_dpp v4, v3 quad_perm:[1,0,3,2] row_mask:0xf bank_mask:0xf
	s_and_saveexec_b64 s[4:5], s[0:1]
	s_cbranch_execz .LBB0_874
	s_waitcnt lgkmcnt(0)
	v_cvt_pk_bf16_f32 v3, v3, v4
	v_add_co_u32_e32 v4, vcc, 0x3c000, v82
	s_nop 1
	v_addc_co_u32_e32 v5, vcc, 0, v83, vcc
	global_store_dword v[4:5], v3, off offset:128
.LBB0_874:
	s_or_b64 exec, exec, s[4:5]
	v_mul_f32_e32 v2, v8, v2
	s_nop 1
	v_mov_b32_dpp v3, v2 quad_perm:[1,0,3,2] row_mask:0xf bank_mask:0xf
	s_and_saveexec_b64 s[4:5], s[0:1]
	s_cbranch_execz .LBB0_876
	s_waitcnt lgkmcnt(0)
	v_cvt_pk_bf16_f32 v4, v2, v3
	v_add_co_u32_e32 v2, vcc, 0x3c000, v82
	s_nop 1
	v_addc_co_u32_e32 v3, vcc, 0, v83, vcc
	global_store_dword v[2:3], v4, off offset:192
.LBB0_876:
	s_or_b64 exec, exec, s[4:5]
	v_rcp_f32_e32 v2, v77
	s_waitcnt lgkmcnt(0)
	v_mul_f32_e32 v3, v57, v2
	s_nop 1
	v_mov_b32_dpp v4, v3 quad_perm:[1,0,3,2] row_mask:0xf bank_mask:0xf
	s_and_saveexec_b64 s[4:5], s[0:1]
	s_cbranch_execz .LBB0_878
	s_waitcnt lgkmcnt(0)
	v_cvt_pk_bf16_f32 v3, v3, v4
	v_add_co_u32_e32 v4, vcc, 0x42000, v82
	s_nop 1
	v_addc_co_u32_e32 v5, vcc, 0, v83, vcc
	global_store_dword v[4:5], v3, off
.LBB0_878:
	s_or_b64 exec, exec, s[4:5]
	v_mul_f32_e32 v3, v41, v2
	s_waitcnt lgkmcnt(0)
	s_nop 1
	v_mov_b32_dpp v4, v3 quad_perm:[1,0,3,2] row_mask:0xf bank_mask:0xf
	s_and_saveexec_b64 s[4:5], s[0:1]
	s_cbranch_execz .LBB0_880
	s_waitcnt lgkmcnt(0)
	v_cvt_pk_bf16_f32 v3, v3, v4
	v_add_co_u32_e32 v4, vcc, 0x42000, v82
	s_nop 1
	v_addc_co_u32_e32 v5, vcc, 0, v83, vcc
	global_store_dword v[4:5], v3, off offset:64
.LBB0_880:
	s_or_b64 exec, exec, s[4:5]
	v_mul_f32_e32 v3, v25, v2
	s_waitcnt lgkmcnt(0)
	s_nop 1
	v_mov_b32_dpp v4, v3 quad_perm:[1,0,3,2] row_mask:0xf bank_mask:0xf
	s_and_saveexec_b64 s[4:5], s[0:1]
	s_cbranch_execz .LBB0_882
	s_waitcnt lgkmcnt(0)
	v_cvt_pk_bf16_f32 v3, v3, v4
	v_add_co_u32_e32 v4, vcc, 0x42000, v82
	s_nop 1
	v_addc_co_u32_e32 v5, vcc, 0, v83, vcc
	global_store_dword v[4:5], v3, off offset:128
.LBB0_882:
	s_or_b64 exec, exec, s[4:5]
	v_mul_f32_e32 v2, v9, v2
	s_nop 1
	v_mov_b32_dpp v3, v2 quad_perm:[1,0,3,2] row_mask:0xf bank_mask:0xf
	s_and_saveexec_b64 s[4:5], s[0:1]
	s_cbranch_execz .LBB0_884
	s_waitcnt lgkmcnt(0)
	v_cvt_pk_bf16_f32 v4, v2, v3
	v_add_co_u32_e32 v2, vcc, 0x42000, v82
	s_nop 1
	v_addc_co_u32_e32 v3, vcc, 0, v83, vcc
	global_store_dword v[2:3], v4, off offset:192
.LBB0_884:
	s_or_b64 exec, exec, s[4:5]
	v_rcp_f32_e32 v2, v70
	s_waitcnt lgkmcnt(0)
	v_mul_f32_e32 v3, v58, v2
	s_nop 1
	v_mov_b32_dpp v4, v3 quad_perm:[1,0,3,2] row_mask:0xf bank_mask:0xf
	s_and_saveexec_b64 s[4:5], s[0:1]
	s_cbranch_execz .LBB0_886
	s_waitcnt lgkmcnt(0)
	v_cvt_pk_bf16_f32 v3, v3, v4
	v_add_co_u32_e32 v4, vcc, 0x60000, v82
	s_nop 1
	v_addc_co_u32_e32 v5, vcc, 0, v83, vcc
	global_store_dword v[4:5], v3, off
.LBB0_886:
	s_or_b64 exec, exec, s[4:5]
	v_mul_f32_e32 v3, v42, v2
	s_waitcnt lgkmcnt(0)
	s_nop 1
	v_mov_b32_dpp v4, v3 quad_perm:[1,0,3,2] row_mask:0xf bank_mask:0xf
	s_and_saveexec_b64 s[4:5], s[0:1]
	s_cbranch_execz .LBB0_888
	s_waitcnt lgkmcnt(0)
	v_cvt_pk_bf16_f32 v3, v3, v4
	v_add_co_u32_e32 v4, vcc, 0x60000, v82
	s_nop 1
	v_addc_co_u32_e32 v5, vcc, 0, v83, vcc
	global_store_dword v[4:5], v3, off offset:64
.LBB0_888:
	s_or_b64 exec, exec, s[4:5]
	v_mul_f32_e32 v3, v26, v2
	s_waitcnt lgkmcnt(0)
	s_nop 1
	v_mov_b32_dpp v4, v3 quad_perm:[1,0,3,2] row_mask:0xf bank_mask:0xf
	s_and_saveexec_b64 s[4:5], s[0:1]
	s_cbranch_execz .LBB0_890
	s_waitcnt lgkmcnt(0)
	v_cvt_pk_bf16_f32 v3, v3, v4
	v_add_co_u32_e32 v4, vcc, 0x60000, v82
	s_nop 1
	v_addc_co_u32_e32 v5, vcc, 0, v83, vcc
	global_store_dword v[4:5], v3, off offset:128
.LBB0_890:
	s_or_b64 exec, exec, s[4:5]
	v_mul_f32_e32 v2, v10, v2
	s_nop 1
	v_mov_b32_dpp v3, v2 quad_perm:[1,0,3,2] row_mask:0xf bank_mask:0xf
	s_and_saveexec_b64 s[4:5], s[0:1]
	s_cbranch_execz .LBB0_892
	s_waitcnt lgkmcnt(0)
	v_cvt_pk_bf16_f32 v4, v2, v3
	v_add_co_u32_e32 v2, vcc, 0x60000, v82
	s_nop 1
	v_addc_co_u32_e32 v3, vcc, 0, v83, vcc
	global_store_dword v[2:3], v4, off offset:192
.LBB0_892:
	s_or_b64 exec, exec, s[4:5]
	v_rcp_f32_e32 v2, v71
	s_waitcnt lgkmcnt(0)
	v_mul_f32_e32 v3, v59, v2
	s_nop 1
	v_mov_b32_dpp v4, v3 quad_perm:[1,0,3,2] row_mask:0xf bank_mask:0xf
	s_and_saveexec_b64 s[4:5], s[0:1]
	s_cbranch_execz .LBB0_894
	s_waitcnt lgkmcnt(0)
	v_cvt_pk_bf16_f32 v3, v3, v4
	v_add_co_u32_e32 v4, vcc, 0x66000, v82
	s_nop 1
	v_addc_co_u32_e32 v5, vcc, 0, v83, vcc
	global_store_dword v[4:5], v3, off
.LBB0_894:
	s_or_b64 exec, exec, s[4:5]
	v_mul_f32_e32 v3, v43, v2
	s_waitcnt lgkmcnt(0)
	s_nop 1
	v_mov_b32_dpp v4, v3 quad_perm:[1,0,3,2] row_mask:0xf bank_mask:0xf
	s_and_saveexec_b64 s[4:5], s[0:1]
	s_cbranch_execz .LBB0_896
	s_waitcnt lgkmcnt(0)
	v_cvt_pk_bf16_f32 v3, v3, v4
	v_add_co_u32_e32 v4, vcc, 0x66000, v82
	s_nop 1
	v_addc_co_u32_e32 v5, vcc, 0, v83, vcc
	global_store_dword v[4:5], v3, off offset:64
.LBB0_896:
	s_or_b64 exec, exec, s[4:5]
	v_mul_f32_e32 v3, v27, v2
	s_waitcnt lgkmcnt(0)
	s_nop 1
	v_mov_b32_dpp v4, v3 quad_perm:[1,0,3,2] row_mask:0xf bank_mask:0xf
	s_and_saveexec_b64 s[4:5], s[0:1]
	s_cbranch_execz .LBB0_898
	s_waitcnt lgkmcnt(0)
	v_cvt_pk_bf16_f32 v3, v3, v4
	v_add_co_u32_e32 v4, vcc, 0x66000, v82
	s_nop 1
	v_addc_co_u32_e32 v5, vcc, 0, v83, vcc
	global_store_dword v[4:5], v3, off offset:128
.LBB0_898:
	s_or_b64 exec, exec, s[4:5]
	v_mul_f32_e32 v2, v11, v2
	s_nop 1
	v_mov_b32_dpp v3, v2 quad_perm:[1,0,3,2] row_mask:0xf bank_mask:0xf
	s_and_saveexec_b64 s[4:5], s[0:1]
	s_cbranch_execz .LBB0_900
	s_waitcnt lgkmcnt(0)
	v_cvt_pk_bf16_f32 v4, v2, v3
	v_add_co_u32_e32 v2, vcc, 0x66000, v82
	s_nop 1
	v_addc_co_u32_e32 v3, vcc, 0, v83, vcc
	global_store_dword v[2:3], v4, off offset:192
.LBB0_900:
	s_or_b64 exec, exec, s[4:5]
	v_rcp_f32_e32 v2, v72
	s_waitcnt lgkmcnt(0)
	v_mul_f32_e32 v3, v60, v2
	s_nop 1
	v_mov_b32_dpp v4, v3 quad_perm:[1,0,3,2] row_mask:0xf bank_mask:0xf
	s_and_saveexec_b64 s[4:5], s[0:1]
	s_cbranch_execz .LBB0_902
	s_waitcnt lgkmcnt(0)
	v_cvt_pk_bf16_f32 v3, v3, v4
	v_add_co_u32_e32 v4, vcc, 0x6c000, v82
	s_nop 1
	v_addc_co_u32_e32 v5, vcc, 0, v83, vcc
	global_store_dword v[4:5], v3, off
.LBB0_902:
	s_or_b64 exec, exec, s[4:5]
	v_mul_f32_e32 v3, v44, v2
	s_waitcnt lgkmcnt(0)
	s_nop 1
	v_mov_b32_dpp v4, v3 quad_perm:[1,0,3,2] row_mask:0xf bank_mask:0xf
	s_and_saveexec_b64 s[4:5], s[0:1]
	s_cbranch_execz .LBB0_904
	s_waitcnt lgkmcnt(0)
	v_cvt_pk_bf16_f32 v3, v3, v4
	v_add_co_u32_e32 v4, vcc, 0x6c000, v82
	s_nop 1
	v_addc_co_u32_e32 v5, vcc, 0, v83, vcc
	global_store_dword v[4:5], v3, off offset:64
.LBB0_904:
	s_or_b64 exec, exec, s[4:5]
	v_mul_f32_e32 v3, v28, v2
	s_waitcnt lgkmcnt(0)
	s_nop 1
	v_mov_b32_dpp v4, v3 quad_perm:[1,0,3,2] row_mask:0xf bank_mask:0xf
	s_and_saveexec_b64 s[4:5], s[0:1]
	s_cbranch_execz .LBB0_906
	s_waitcnt lgkmcnt(0)
	v_cvt_pk_bf16_f32 v3, v3, v4
	v_add_co_u32_e32 v4, vcc, 0x6c000, v82
	s_nop 1
	v_addc_co_u32_e32 v5, vcc, 0, v83, vcc
	global_store_dword v[4:5], v3, off offset:128
.LBB0_906:
	s_or_b64 exec, exec, s[4:5]
	v_mul_f32_e32 v2, v12, v2
	s_nop 1
	v_mov_b32_dpp v3, v2 quad_perm:[1,0,3,2] row_mask:0xf bank_mask:0xf
	s_and_saveexec_b64 s[4:5], s[0:1]
	s_cbranch_execz .LBB0_908
	s_waitcnt lgkmcnt(0)
	v_cvt_pk_bf16_f32 v4, v2, v3
	v_add_co_u32_e32 v2, vcc, 0x6c000, v82
	s_nop 1
	v_addc_co_u32_e32 v3, vcc, 0, v83, vcc
	global_store_dword v[2:3], v4, off offset:192
.LBB0_908:
	s_or_b64 exec, exec, s[4:5]
	v_rcp_f32_e32 v2, v73
	s_waitcnt lgkmcnt(0)
	v_mul_f32_e32 v3, v61, v2
	s_nop 1
	v_mov_b32_dpp v4, v3 quad_perm:[1,0,3,2] row_mask:0xf bank_mask:0xf
	s_and_saveexec_b64 s[4:5], s[0:1]
	s_cbranch_execz .LBB0_910
	s_waitcnt lgkmcnt(0)
	v_cvt_pk_bf16_f32 v3, v3, v4
	v_add_co_u32_e32 v4, vcc, 0x72000, v82
	s_nop 1
	v_addc_co_u32_e32 v5, vcc, 0, v83, vcc
	global_store_dword v[4:5], v3, off
.LBB0_910:
	s_or_b64 exec, exec, s[4:5]
	v_mul_f32_e32 v3, v45, v2
	s_waitcnt lgkmcnt(0)
	s_nop 1
	v_mov_b32_dpp v4, v3 quad_perm:[1,0,3,2] row_mask:0xf bank_mask:0xf
	s_and_saveexec_b64 s[4:5], s[0:1]
	s_cbranch_execz .LBB0_912
	s_waitcnt lgkmcnt(0)
	v_cvt_pk_bf16_f32 v3, v3, v4
	v_add_co_u32_e32 v4, vcc, 0x72000, v82
	s_nop 1
	v_addc_co_u32_e32 v5, vcc, 0, v83, vcc
	global_store_dword v[4:5], v3, off offset:64
.LBB0_912:
	s_or_b64 exec, exec, s[4:5]
	v_mul_f32_e32 v3, v29, v2
	s_waitcnt lgkmcnt(0)
	s_nop 1
	v_mov_b32_dpp v4, v3 quad_perm:[1,0,3,2] row_mask:0xf bank_mask:0xf
	s_and_saveexec_b64 s[4:5], s[0:1]
	s_cbranch_execz .LBB0_914
	s_waitcnt lgkmcnt(0)
	v_cvt_pk_bf16_f32 v3, v3, v4
	v_add_co_u32_e32 v4, vcc, 0x72000, v82
	s_nop 1
	v_addc_co_u32_e32 v5, vcc, 0, v83, vcc
	global_store_dword v[4:5], v3, off offset:128
.LBB0_914:
	s_or_b64 exec, exec, s[4:5]
	v_mul_f32_e32 v2, v13, v2
	s_nop 1
	v_mov_b32_dpp v3, v2 quad_perm:[1,0,3,2] row_mask:0xf bank_mask:0xf
	s_and_saveexec_b64 s[4:5], s[0:1]
	s_cbranch_execz .LBB0_916
	s_waitcnt lgkmcnt(0)
	v_cvt_pk_bf16_f32 v4, v2, v3
	v_add_co_u32_e32 v2, vcc, 0x72000, v82
	s_nop 1
	v_addc_co_u32_e32 v3, vcc, 0, v83, vcc
	global_store_dword v[2:3], v4, off offset:192
.LBB0_916:
	s_or_b64 exec, exec, s[4:5]
	v_rcp_f32_e32 v2, v66
	s_waitcnt lgkmcnt(0)
	v_mul_f32_e32 v3, v62, v2
	s_nop 1
	v_mov_b32_dpp v4, v3 quad_perm:[1,0,3,2] row_mask:0xf bank_mask:0xf
	s_and_saveexec_b64 s[4:5], s[0:1]
	s_cbranch_execz .LBB0_918
	s_waitcnt lgkmcnt(0)
	v_cvt_pk_bf16_f32 v3, v3, v4
	v_add_co_u32_e32 v4, vcc, 0x90000, v82
	s_nop 1
	v_addc_co_u32_e32 v5, vcc, 0, v83, vcc
	global_store_dword v[4:5], v3, off
.LBB0_918:
	s_or_b64 exec, exec, s[4:5]
	v_mul_f32_e32 v3, v46, v2
	s_waitcnt lgkmcnt(0)
	s_nop 1
	v_mov_b32_dpp v4, v3 quad_perm:[1,0,3,2] row_mask:0xf bank_mask:0xf
	s_and_saveexec_b64 s[4:5], s[0:1]
	s_cbranch_execz .LBB0_920
	s_waitcnt lgkmcnt(0)
	v_cvt_pk_bf16_f32 v3, v3, v4
	v_add_co_u32_e32 v4, vcc, 0x90000, v82
	s_nop 1
	v_addc_co_u32_e32 v5, vcc, 0, v83, vcc
	global_store_dword v[4:5], v3, off offset:64
.LBB0_920:
	s_or_b64 exec, exec, s[4:5]
	v_mul_f32_e32 v3, v30, v2
	s_waitcnt lgkmcnt(0)
	s_nop 1
	v_mov_b32_dpp v4, v3 quad_perm:[1,0,3,2] row_mask:0xf bank_mask:0xf
	s_and_saveexec_b64 s[4:5], s[0:1]
	s_cbranch_execz .LBB0_922
	s_waitcnt lgkmcnt(0)
	v_cvt_pk_bf16_f32 v3, v3, v4
	v_add_co_u32_e32 v4, vcc, 0x90000, v82
	s_nop 1
	v_addc_co_u32_e32 v5, vcc, 0, v83, vcc
	global_store_dword v[4:5], v3, off offset:128
.LBB0_922:
	s_or_b64 exec, exec, s[4:5]
	v_mul_f32_e32 v2, v14, v2
	s_nop 1
	v_mov_b32_dpp v3, v2 quad_perm:[1,0,3,2] row_mask:0xf bank_mask:0xf
	s_and_saveexec_b64 s[4:5], s[0:1]
	s_cbranch_execz .LBB0_924
	s_waitcnt lgkmcnt(0)
	v_cvt_pk_bf16_f32 v4, v2, v3
	v_add_co_u32_e32 v2, vcc, 0x90000, v82
	s_nop 1
	v_addc_co_u32_e32 v3, vcc, 0, v83, vcc
	global_store_dword v[2:3], v4, off offset:192
.LBB0_924:
	s_or_b64 exec, exec, s[4:5]
	v_rcp_f32_e32 v2, v67
	s_waitcnt lgkmcnt(0)
	v_mul_f32_e32 v3, v63, v2
	s_nop 1
	v_mov_b32_dpp v4, v3 quad_perm:[1,0,3,2] row_mask:0xf bank_mask:0xf
	s_and_saveexec_b64 s[4:5], s[0:1]
	s_cbranch_execz .LBB0_926
	s_waitcnt lgkmcnt(0)
	v_cvt_pk_bf16_f32 v3, v3, v4
	v_add_co_u32_e32 v4, vcc, 0x96000, v82
	s_nop 1
	v_addc_co_u32_e32 v5, vcc, 0, v83, vcc
	global_store_dword v[4:5], v3, off
.LBB0_926:
	s_or_b64 exec, exec, s[4:5]
	v_mul_f32_e32 v3, v47, v2
	s_waitcnt lgkmcnt(0)
	s_nop 1
	v_mov_b32_dpp v4, v3 quad_perm:[1,0,3,2] row_mask:0xf bank_mask:0xf
	s_and_saveexec_b64 s[4:5], s[0:1]
	s_cbranch_execz .LBB0_928
	s_waitcnt lgkmcnt(0)
	v_cvt_pk_bf16_f32 v3, v3, v4
	v_add_co_u32_e32 v4, vcc, 0x96000, v82
	s_nop 1
	v_addc_co_u32_e32 v5, vcc, 0, v83, vcc
	global_store_dword v[4:5], v3, off offset:64
.LBB0_928:
	s_or_b64 exec, exec, s[4:5]
	v_mul_f32_e32 v3, v31, v2
	s_waitcnt lgkmcnt(0)
	s_nop 1
	v_mov_b32_dpp v4, v3 quad_perm:[1,0,3,2] row_mask:0xf bank_mask:0xf
	s_and_saveexec_b64 s[4:5], s[0:1]
	s_cbranch_execz .LBB0_930
	s_waitcnt lgkmcnt(0)
	v_cvt_pk_bf16_f32 v3, v3, v4
	v_add_co_u32_e32 v4, vcc, 0x96000, v82
	s_nop 1
	v_addc_co_u32_e32 v5, vcc, 0, v83, vcc
	global_store_dword v[4:5], v3, off offset:128
.LBB0_930:
	s_or_b64 exec, exec, s[4:5]
	v_mul_f32_e32 v2, v15, v2
	s_nop 1
	v_mov_b32_dpp v3, v2 quad_perm:[1,0,3,2] row_mask:0xf bank_mask:0xf
	s_and_saveexec_b64 s[4:5], s[0:1]
	s_cbranch_execz .LBB0_932
	s_waitcnt lgkmcnt(0)
	v_cvt_pk_bf16_f32 v4, v2, v3
	v_add_co_u32_e32 v2, vcc, 0x96000, v82
	s_nop 1
	v_addc_co_u32_e32 v3, vcc, 0, v83, vcc
	global_store_dword v[2:3], v4, off offset:192
.LBB0_932:
	s_or_b64 exec, exec, s[4:5]
	v_rcp_f32_e32 v2, v68
	s_waitcnt lgkmcnt(0)
	v_mul_f32_e32 v3, v64, v2
	s_nop 1
	v_mov_b32_dpp v4, v3 quad_perm:[1,0,3,2] row_mask:0xf bank_mask:0xf
	s_and_saveexec_b64 s[4:5], s[0:1]
	s_cbranch_execz .LBB0_934
	s_waitcnt lgkmcnt(0)
	v_cvt_pk_bf16_f32 v3, v3, v4
	v_add_co_u32_e32 v4, vcc, 0x9c000, v82
	s_nop 1
	v_addc_co_u32_e32 v5, vcc, 0, v83, vcc
	global_store_dword v[4:5], v3, off
.LBB0_934:
	s_or_b64 exec, exec, s[4:5]
	v_mul_f32_e32 v3, v48, v2
	s_waitcnt lgkmcnt(0)
	s_nop 1
	v_mov_b32_dpp v4, v3 quad_perm:[1,0,3,2] row_mask:0xf bank_mask:0xf
	s_and_saveexec_b64 s[4:5], s[0:1]
	s_cbranch_execz .LBB0_936
	s_waitcnt lgkmcnt(0)
	v_cvt_pk_bf16_f32 v3, v3, v4
	v_add_co_u32_e32 v4, vcc, 0x9c000, v82
	s_nop 1
	v_addc_co_u32_e32 v5, vcc, 0, v83, vcc
	global_store_dword v[4:5], v3, off offset:64
.LBB0_936:
	s_or_b64 exec, exec, s[4:5]
	v_mul_f32_e32 v3, v32, v2
	s_waitcnt lgkmcnt(0)
	s_nop 1
	v_mov_b32_dpp v4, v3 quad_perm:[1,0,3,2] row_mask:0xf bank_mask:0xf
	s_and_saveexec_b64 s[4:5], s[0:1]
	s_cbranch_execz .LBB0_938
	s_waitcnt lgkmcnt(0)
	v_cvt_pk_bf16_f32 v3, v3, v4
	v_add_co_u32_e32 v4, vcc, 0x9c000, v82
	s_nop 1
	v_addc_co_u32_e32 v5, vcc, 0, v83, vcc
	global_store_dword v[4:5], v3, off offset:128
.LBB0_938:
	s_or_b64 exec, exec, s[4:5]
	v_mul_f32_e32 v2, v16, v2
	s_nop 1
	v_mov_b32_dpp v3, v2 quad_perm:[1,0,3,2] row_mask:0xf bank_mask:0xf
	s_and_saveexec_b64 s[4:5], s[0:1]
	s_cbranch_execz .LBB0_940
	s_waitcnt lgkmcnt(0)
	v_cvt_pk_bf16_f32 v4, v2, v3
	v_add_co_u32_e32 v2, vcc, 0x9c000, v82
	s_nop 1
	v_addc_co_u32_e32 v3, vcc, 0, v83, vcc
	global_store_dword v[2:3], v4, off offset:192
.LBB0_940:
	s_or_b64 exec, exec, s[4:5]
	v_rcp_f32_e32 v2, v69
	s_waitcnt lgkmcnt(0)
	v_mul_f32_e32 v3, v65, v2
	s_nop 1
	v_mov_b32_dpp v4, v3 quad_perm:[1,0,3,2] row_mask:0xf bank_mask:0xf
	s_and_saveexec_b64 s[4:5], s[0:1]
	s_cbranch_execz .LBB0_942
	s_waitcnt lgkmcnt(0)
	v_cvt_pk_bf16_f32 v3, v3, v4
	v_add_co_u32_e32 v4, vcc, 0xa2000, v82
	s_nop 1
	v_addc_co_u32_e32 v5, vcc, 0, v83, vcc
	global_store_dword v[4:5], v3, off
.LBB0_942:
	s_or_b64 exec, exec, s[4:5]
	v_mul_f32_e32 v3, v49, v2
	s_waitcnt lgkmcnt(0)
	s_nop 1
	v_mov_b32_dpp v4, v3 quad_perm:[1,0,3,2] row_mask:0xf bank_mask:0xf
	s_and_saveexec_b64 s[4:5], s[0:1]
	s_cbranch_execz .LBB0_944
	s_waitcnt lgkmcnt(0)
	v_cvt_pk_bf16_f32 v3, v3, v4
	v_add_co_u32_e32 v4, vcc, 0xa2000, v82
	s_nop 1
	v_addc_co_u32_e32 v5, vcc, 0, v83, vcc
	global_store_dword v[4:5], v3, off offset:64
.LBB0_944:
	s_or_b64 exec, exec, s[4:5]
	v_mul_f32_e32 v3, v33, v2
	s_waitcnt lgkmcnt(0)
	s_nop 1
	v_mov_b32_dpp v4, v3 quad_perm:[1,0,3,2] row_mask:0xf bank_mask:0xf
	s_and_saveexec_b64 s[4:5], s[0:1]
	s_cbranch_execz .LBB0_946
	s_waitcnt lgkmcnt(0)
	v_cvt_pk_bf16_f32 v3, v3, v4
	v_add_co_u32_e32 v4, vcc, 0xa2000, v82
	s_nop 1
	v_addc_co_u32_e32 v5, vcc, 0, v83, vcc
	global_store_dword v[4:5], v3, off offset:128
.LBB0_946:
	s_or_b64 exec, exec, s[4:5]
	v_mul_f32_e32 v2, v17, v2
	s_nop 1
	v_mov_b32_dpp v3, v2 quad_perm:[1,0,3,2] row_mask:0xf bank_mask:0xf
	s_and_saveexec_b64 s[4:5], s[0:1]
	s_cbranch_execz .LBB0_948
	s_waitcnt lgkmcnt(0)
	v_cvt_pk_bf16_f32 v4, v2, v3
	v_add_co_u32_e32 v2, vcc, 0xa2000, v82
	s_nop 1
	v_addc_co_u32_e32 v3, vcc, 0, v83, vcc
	global_store_dword v[2:3], v4, off offset:192

.LBB0_972:
	s_or_b64 exec, exec, s[4:5]
	v_lshl_add_u32 v66, v157, 2, s66
	ds_read_b128 v[78:81], v66
	ds_read_b128 v[74:77], v66 offset:32
	s_mul_hi_i32 s0, s18, 0x1800
	s_mulk_i32 s18, 0x1800
	s_add_u32 s1, s58, s18
	s_waitcnt lgkmcnt(1)
	v_rcp_f32_e32 v78, v78
	s_addc_u32 s0, s59, s0
	s_add_u32 s1, s1, s60
	s_addc_u32 s0, s0, 0
	s_mul_hi_i32 s3, s61, 0x18000
	s_mul_i32 s61, s61, 0x18000
	v_mul_f32_e32 v2, v2, v78
	ds_read_b128 v[70:73], v66 offset:64
	ds_read_b128 v[66:69], v66 offset:96
	s_add_u32 s2, s1, s61
	s_nop 1
	v_mov_b32_dpp v84, v2 quad_perm:[1,0,3,2] row_mask:0xf bank_mask:0xf
	s_addc_u32 s3, s0, s3
	v_and_b32_e32 v82, 1, v155
	v_lshlrev_b32_e32 v162, 1, v156
	v_cmp_eq_u32_e64 s[0:1], 0, v82
	v_lshl_add_u64 v[82:83], s[2:3], 0, v[162:163]
	v_mul_u32_u24_e32 v162, 0x60000, v154
	v_lshl_add_u64 v[82:83], v[82:83], 0, v[162:163]
	v_lshl_add_u64 v[82:83], v[82:83], 0, s[26:27]
	s_and_saveexec_b64 s[2:3], s[0:1]
	s_cbranch_execz .LBB0_974
	s_waitcnt lgkmcnt(0)
	v_cvt_pk_bf16_f32 v2, v2, v84
	global_store_dword v[82:83], v2, off
.LBB0_974:
	s_or_b64 exec, exec, s[2:3]
	v_mul_f32_e32 v2, v18, v78
	s_nop 1
	v_mov_b32_dpp v18, v2 quad_perm:[1,0,3,2] row_mask:0xf bank_mask:0xf
	s_and_saveexec_b64 s[2:3], s[0:1]
	s_cbranch_execz .LBB0_976
	s_waitcnt lgkmcnt(0)
	v_cvt_pk_bf16_f32 v2, v2, v18
	global_store_dword v[82:83], v2, off offset:64
.LBB0_976:
	s_or_b64 exec, exec, s[2:3]
	v_mul_f32_e32 v2, v34, v78
	s_waitcnt lgkmcnt(0)
	s_nop 1
	v_mov_b32_dpp v18, v2 quad_perm:[1,0,3,2] row_mask:0xf bank_mask:0xf
	s_and_saveexec_b64 s[2:3], s[0:1]
	s_cbranch_execz .LBB0_978
	s_waitcnt lgkmcnt(0)
	v_cvt_pk_bf16_f32 v2, v2, v18
	global_store_dword v[82:83], v2, off offset:128
.LBB0_978:
	s_or_b64 exec, exec, s[2:3]
	v_mul_f32_e32 v2, v50, v78
	s_waitcnt lgkmcnt(0)
	s_nop 1
	v_mov_b32_dpp v18, v2 quad_perm:[1,0,3,2] row_mask:0xf bank_mask:0xf
	s_and_saveexec_b64 s[2:3], s[0:1]
	s_cbranch_execz .LBB0_980
	s_waitcnt lgkmcnt(0)
	v_cvt_pk_bf16_f32 v2, v2, v18
	global_store_dword v[82:83], v2, off offset:192
.LBB0_980:
	s_or_b64 exec, exec, s[2:3]
	v_rcp_f32_e32 v2, v79
	s_nop 0
	v_mul_f32_e32 v3, v3, v2
	s_waitcnt lgkmcnt(0)
	s_nop 1
	v_mov_b32_dpp v18, v3 quad_perm:[1,0,3,2] row_mask:0xf bank_mask:0xf
	s_and_saveexec_b64 s[2:3], s[0:1]
	s_cbranch_execz .LBB0_982
	v_add_co_u32_e32 v78, vcc, 0x18000, v82
	s_waitcnt lgkmcnt(0)
	v_cvt_pk_bf16_f32 v3, v3, v18
	s_nop 0
	v_addc_co_u32_e32 v79, vcc, 0, v83, vcc
	global_store_dword v[78:79], v3, off
.LBB0_982:
	s_or_b64 exec, exec, s[2:3]
	v_mul_f32_e32 v3, v19, v2
	s_waitcnt lgkmcnt(0)
	s_nop 1
	v_mov_b32_dpp v18, v3 quad_perm:[1,0,3,2] row_mask:0xf bank_mask:0xf
	s_and_saveexec_b64 s[2:3], s[0:1]
	s_cbranch_execz .LBB0_984
	s_waitcnt lgkmcnt(0)
	v_cvt_pk_bf16_f32 v3, v3, v18
	v_add_co_u32_e32 v18, vcc, 0x18000, v82
	s_nop 1
	v_addc_co_u32_e32 v19, vcc, 0, v83, vcc
	global_store_dword v[18:19], v3, off offset:64
.LBB0_984:
	s_or_b64 exec, exec, s[2:3]
	v_mul_f32_e32 v3, v35, v2
	s_waitcnt lgkmcnt(0)
	s_nop 1
	v_mov_b32_dpp v18, v3 quad_perm:[1,0,3,2] row_mask:0xf bank_mask:0xf
	s_and_saveexec_b64 s[2:3], s[0:1]
	s_cbranch_execz .LBB0_986
	s_waitcnt lgkmcnt(0)
	v_cvt_pk_bf16_f32 v3, v3, v18
	v_add_co_u32_e32 v18, vcc, 0x18000, v82
	s_nop 1
	v_addc_co_u32_e32 v19, vcc, 0, v83, vcc
	global_store_dword v[18:19], v3, off offset:128
.LBB0_986:
	s_or_b64 exec, exec, s[2:3]
	v_mul_f32_e32 v2, v51, v2
	s_nop 1
	v_mov_b32_dpp v3, v2 quad_perm:[1,0,3,2] row_mask:0xf bank_mask:0xf
	s_and_saveexec_b64 s[2:3], s[0:1]
	s_cbranch_execz .LBB0_988
	s_waitcnt lgkmcnt(0)
	v_cvt_pk_bf16_f32 v18, v2, v3
	v_add_co_u32_e32 v2, vcc, 0x18000, v82
	s_nop 1
	v_addc_co_u32_e32 v3, vcc, 0, v83, vcc
	global_store_dword v[2:3], v18, off offset:192
.LBB0_988:
	s_or_b64 exec, exec, s[2:3]
	v_rcp_f32_e32 v2, v80
	s_waitcnt lgkmcnt(0)
	v_mul_f32_e32 v3, v4, v2
	s_nop 1
	v_mov_b32_dpp v4, v3 quad_perm:[1,0,3,2] row_mask:0xf bank_mask:0xf
	s_and_saveexec_b64 s[2:3], s[0:1]
	s_cbranch_execz .LBB0_990
	v_add_co_u32_e32 v18, vcc, 0x30000, v82
	s_waitcnt lgkmcnt(0)
	v_cvt_pk_bf16_f32 v3, v3, v4
	s_nop 0
	v_addc_co_u32_e32 v19, vcc, 0, v83, vcc
	global_store_dword v[18:19], v3, off
.LBB0_990:
	s_or_b64 exec, exec, s[2:3]
	v_mul_f32_e32 v3, v20, v2
	s_waitcnt lgkmcnt(0)
	s_nop 1
	v_mov_b32_dpp v4, v3 quad_perm:[1,0,3,2] row_mask:0xf bank_mask:0xf
	s_and_saveexec_b64 s[2:3], s[0:1]
	s_cbranch_execz .LBB0_992
	v_add_co_u32_e32 v18, vcc, 0x30000, v82
	s_waitcnt lgkmcnt(0)
	v_cvt_pk_bf16_f32 v3, v3, v4
	s_nop 0
	v_addc_co_u32_e32 v19, vcc, 0, v83, vcc
	global_store_dword v[18:19], v3, off offset:64
.LBB0_992:
	s_or_b64 exec, exec, s[2:3]
	v_mul_f32_e32 v3, v36, v2
	s_waitcnt lgkmcnt(0)
	s_nop 1
	v_mov_b32_dpp v4, v3 quad_perm:[1,0,3,2] row_mask:0xf bank_mask:0xf
	s_and_saveexec_b64 s[2:3], s[0:1]
	s_cbranch_execz .LBB0_994
	v_add_co_u32_e32 v18, vcc, 0x30000, v82
	s_waitcnt lgkmcnt(0)
	v_cvt_pk_bf16_f32 v3, v3, v4
	s_nop 0
	v_addc_co_u32_e32 v19, vcc, 0, v83, vcc
	global_store_dword v[18:19], v3, off offset:128
.LBB0_994:
	s_or_b64 exec, exec, s[2:3]
	v_mul_f32_e32 v2, v52, v2
	s_nop 1
	v_mov_b32_dpp v3, v2 quad_perm:[1,0,3,2] row_mask:0xf bank_mask:0xf
	s_and_saveexec_b64 s[2:3], s[0:1]
	s_cbranch_execz .LBB0_996
	s_waitcnt lgkmcnt(0)
	v_cvt_pk_bf16_f32 v4, v2, v3
	v_add_co_u32_e32 v2, vcc, 0x30000, v82
	s_nop 1
	v_addc_co_u32_e32 v3, vcc, 0, v83, vcc
	global_store_dword v[2:3], v4, off offset:192
.LBB0_996:
	s_or_b64 exec, exec, s[2:3]
	v_rcp_f32_e32 v2, v81
	s_waitcnt lgkmcnt(0)
	v_mul_f32_e32 v3, v5, v2
	s_nop 1
	v_mov_b32_dpp v4, v3 quad_perm:[1,0,3,2] row_mask:0xf bank_mask:0xf
	s_and_saveexec_b64 s[2:3], s[0:1]
	s_cbranch_execz .LBB0_998
	s_waitcnt lgkmcnt(0)
	v_cvt_pk_bf16_f32 v3, v3, v4
	v_add_co_u32_e32 v4, vcc, 0x48000, v82
	s_nop 1
	v_addc_co_u32_e32 v5, vcc, 0, v83, vcc
	global_store_dword v[4:5], v3, off
.LBB0_998:
	s_or_b64 exec, exec, s[2:3]
	v_mul_f32_e32 v3, v21, v2
	s_waitcnt lgkmcnt(0)
	s_nop 1
	v_mov_b32_dpp v4, v3 quad_perm:[1,0,3,2] row_mask:0xf bank_mask:0xf
	s_and_saveexec_b64 s[2:3], s[0:1]
	s_cbranch_execz .LBB0_1000
	s_waitcnt lgkmcnt(0)
	v_cvt_pk_bf16_f32 v3, v3, v4
	v_add_co_u32_e32 v4, vcc, 0x48000, v82
	s_nop 1
	v_addc_co_u32_e32 v5, vcc, 0, v83, vcc
	global_store_dword v[4:5], v3, off offset:64
.LBB0_1000:
	s_or_b64 exec, exec, s[2:3]
	v_mul_f32_e32 v3, v37, v2
	s_waitcnt lgkmcnt(0)
	s_nop 1
	v_mov_b32_dpp v4, v3 quad_perm:[1,0,3,2] row_mask:0xf bank_mask:0xf
	s_and_saveexec_b64 s[2:3], s[0:1]
	s_cbranch_execz .LBB0_1002
	s_waitcnt lgkmcnt(0)
	v_cvt_pk_bf16_f32 v3, v3, v4
	v_add_co_u32_e32 v4, vcc, 0x48000, v82
	s_nop 1
	v_addc_co_u32_e32 v5, vcc, 0, v83, vcc
	global_store_dword v[4:5], v3, off offset:128
.LBB0_1002:
	s_or_b64 exec, exec, s[2:3]
	v_mul_f32_e32 v2, v53, v2
	s_nop 1
	v_mov_b32_dpp v3, v2 quad_perm:[1,0,3,2] row_mask:0xf bank_mask:0xf
	s_and_saveexec_b64 s[2:3], s[0:1]
	s_cbranch_execz .LBB0_1004
	s_waitcnt lgkmcnt(0)
	v_cvt_pk_bf16_f32 v4, v2, v3
	v_add_co_u32_e32 v2, vcc, 0x48000, v82
	s_nop 1
	v_addc_co_u32_e32 v3, vcc, 0, v83, vcc
	global_store_dword v[2:3], v4, off offset:192
.LBB0_1004:
	s_or_b64 exec, exec, s[2:3]
	v_rcp_f32_e32 v2, v74
	s_waitcnt lgkmcnt(0)
	v_mul_f32_e32 v3, v6, v2
	s_nop 1
	v_mov_b32_dpp v4, v3 quad_perm:[1,0,3,2] row_mask:0xf bank_mask:0xf
	s_and_saveexec_b64 s[2:3], s[0:1]
	s_cbranch_execz .LBB0_1006
	s_waitcnt lgkmcnt(0)
	v_cvt_pk_bf16_f32 v3, v3, v4
	v_add_co_u32_e32 v4, vcc, 0xc0000, v82
	s_nop 1
	v_addc_co_u32_e32 v5, vcc, 0, v83, vcc
	global_store_dword v[4:5], v3, off
.LBB0_1006:
	s_or_b64 exec, exec, s[2:3]
	v_mul_f32_e32 v3, v22, v2
	s_waitcnt lgkmcnt(0)
	s_nop 1
	v_mov_b32_dpp v4, v3 quad_perm:[1,0,3,2] row_mask:0xf bank_mask:0xf
	s_and_saveexec_b64 s[2:3], s[0:1]
	s_cbranch_execz .LBB0_1008
	s_waitcnt lgkmcnt(0)
	v_cvt_pk_bf16_f32 v3, v3, v4
	v_add_co_u32_e32 v4, vcc, 0xc0000, v82
	s_nop 1
	v_addc_co_u32_e32 v5, vcc, 0, v83, vcc
	global_store_dword v[4:5], v3, off offset:64
.LBB0_1008:
	s_or_b64 exec, exec, s[2:3]
	v_mul_f32_e32 v3, v38, v2
	s_waitcnt lgkmcnt(0)
	s_nop 1
	v_mov_b32_dpp v4, v3 quad_perm:[1,0,3,2] row_mask:0xf bank_mask:0xf
	s_and_saveexec_b64 s[2:3], s[0:1]
	s_cbranch_execz .LBB0_1010
	s_waitcnt lgkmcnt(0)
	v_cvt_pk_bf16_f32 v3, v3, v4
	v_add_co_u32_e32 v4, vcc, 0xc0000, v82
	s_nop 1
	v_addc_co_u32_e32 v5, vcc, 0, v83, vcc
	global_store_dword v[4:5], v3, off offset:128
.LBB0_1010:
	s_or_b64 exec, exec, s[2:3]
	v_mul_f32_e32 v2, v54, v2
	s_nop 1
	v_mov_b32_dpp v3, v2 quad_perm:[1,0,3,2] row_mask:0xf bank_mask:0xf
	s_and_saveexec_b64 s[2:3], s[0:1]
	s_cbranch_execz .LBB0_1012
	s_waitcnt lgkmcnt(0)
	v_cvt_pk_bf16_f32 v4, v2, v3
	v_add_co_u32_e32 v2, vcc, 0xc0000, v82
	s_nop 1
	v_addc_co_u32_e32 v3, vcc, 0, v83, vcc
	global_store_dword v[2:3], v4, off offset:192
.LBB0_1012:
	s_or_b64 exec, exec, s[2:3]
	v_rcp_f32_e32 v2, v75
	s_waitcnt lgkmcnt(0)
	v_mul_f32_e32 v3, v7, v2
	s_nop 1
	v_mov_b32_dpp v4, v3 quad_perm:[1,0,3,2] row_mask:0xf bank_mask:0xf
	s_and_saveexec_b64 s[2:3], s[0:1]
	s_cbranch_execz .LBB0_1014
	s_waitcnt lgkmcnt(0)
	v_cvt_pk_bf16_f32 v3, v3, v4
	v_add_co_u32_e32 v4, vcc, 0xd8000, v82
	s_nop 1
	v_addc_co_u32_e32 v5, vcc, 0, v83, vcc
	global_store_dword v[4:5], v3, off
.LBB0_1014:
	s_or_b64 exec, exec, s[2:3]
	v_mul_f32_e32 v3, v23, v2
	s_waitcnt lgkmcnt(0)
	s_nop 1
	v_mov_b32_dpp v4, v3 quad_perm:[1,0,3,2] row_mask:0xf bank_mask:0xf
	s_and_saveexec_b64 s[2:3], s[0:1]
	s_cbranch_execz .LBB0_1016
	s_waitcnt lgkmcnt(0)
	v_cvt_pk_bf16_f32 v3, v3, v4
	v_add_co_u32_e32 v4, vcc, 0xd8000, v82
	s_nop 1
	v_addc_co_u32_e32 v5, vcc, 0, v83, vcc
	global_store_dword v[4:5], v3, off offset:64
.LBB0_1016:
	s_or_b64 exec, exec, s[2:3]
	v_mul_f32_e32 v3, v39, v2
	s_waitcnt lgkmcnt(0)
	s_nop 1
	v_mov_b32_dpp v4, v3 quad_perm:[1,0,3,2] row_mask:0xf bank_mask:0xf
	s_and_saveexec_b64 s[2:3], s[0:1]
	s_cbranch_execz .LBB0_1018
	s_waitcnt lgkmcnt(0)
	v_cvt_pk_bf16_f32 v3, v3, v4
	v_add_co_u32_e32 v4, vcc, 0xd8000, v82
	s_nop 1
	v_addc_co_u32_e32 v5, vcc, 0, v83, vcc
	global_store_dword v[4:5], v3, off offset:128
.LBB0_1018:
	s_or_b64 exec, exec, s[2:3]
	v_mul_f32_e32 v2, v55, v2
	s_nop 1
	v_mov_b32_dpp v3, v2 quad_perm:[1,0,3,2] row_mask:0xf bank_mask:0xf
	s_and_saveexec_b64 s[2:3], s[0:1]
	s_cbranch_execz .LBB0_1020
	s_waitcnt lgkmcnt(0)
	v_cvt_pk_bf16_f32 v4, v2, v3
	v_add_co_u32_e32 v2, vcc, 0xd8000, v82
	s_nop 1
	v_addc_co_u32_e32 v3, vcc, 0, v83, vcc
	global_store_dword v[2:3], v4, off offset:192
.LBB0_1020:
	s_or_b64 exec, exec, s[2:3]
	v_rcp_f32_e32 v2, v76
	s_waitcnt lgkmcnt(0)
	v_mul_f32_e32 v3, v8, v2
	s_nop 1
	v_mov_b32_dpp v4, v3 quad_perm:[1,0,3,2] row_mask:0xf bank_mask:0xf
	s_and_saveexec_b64 s[2:3], s[0:1]
	s_cbranch_execz .LBB0_1022
	s_waitcnt lgkmcnt(0)
	v_cvt_pk_bf16_f32 v3, v3, v4
	v_add_co_u32_e32 v4, vcc, 0xf0000, v82
	s_nop 1
	v_addc_co_u32_e32 v5, vcc, 0, v83, vcc
	global_store_dword v[4:5], v3, off
.LBB0_1022:
	s_or_b64 exec, exec, s[2:3]
	v_mul_f32_e32 v3, v24, v2
	s_waitcnt lgkmcnt(0)
	s_nop 1
	v_mov_b32_dpp v4, v3 quad_perm:[1,0,3,2] row_mask:0xf bank_mask:0xf
	s_and_saveexec_b64 s[2:3], s[0:1]
	s_cbranch_execz .LBB0_1024
	s_waitcnt lgkmcnt(0)
	v_cvt_pk_bf16_f32 v3, v3, v4
	v_add_co_u32_e32 v4, vcc, 0xf0000, v82
	s_nop 1
	v_addc_co_u32_e32 v5, vcc, 0, v83, vcc
	global_store_dword v[4:5], v3, off offset:64
.LBB0_1024:
	s_or_b64 exec, exec, s[2:3]
	v_mul_f32_e32 v3, v40, v2
	s_waitcnt lgkmcnt(0)
	s_nop 1
	v_mov_b32_dpp v4, v3 quad_perm:[1,0,3,2] row_mask:0xf bank_mask:0xf
	s_and_saveexec_b64 s[2:3], s[0:1]
	s_cbranch_execz .LBB0_1026
	s_waitcnt lgkmcnt(0)
	v_cvt_pk_bf16_f32 v3, v3, v4
	v_add_co_u32_e32 v4, vcc, 0xf0000, v82
	s_nop 1
	v_addc_co_u32_e32 v5, vcc, 0, v83, vcc
	global_store_dword v[4:5], v3, off offset:128
.LBB0_1026:
	s_or_b64 exec, exec, s[2:3]
	v_mul_f32_e32 v2, v56, v2
	s_nop 1
	v_mov_b32_dpp v3, v2 quad_perm:[1,0,3,2] row_mask:0xf bank_mask:0xf
	s_and_saveexec_b64 s[2:3], s[0:1]
	s_cbranch_execz .LBB0_1028
	s_waitcnt lgkmcnt(0)
	v_cvt_pk_bf16_f32 v4, v2, v3
	v_add_co_u32_e32 v2, vcc, 0xf0000, v82
	s_nop 1
	v_addc_co_u32_e32 v3, vcc, 0, v83, vcc
	global_store_dword v[2:3], v4, off offset:192
.LBB0_1028:
	s_or_b64 exec, exec, s[2:3]
	v_rcp_f32_e32 v2, v77
	s_waitcnt lgkmcnt(0)
	v_mul_f32_e32 v3, v9, v2
	s_nop 1
	v_mov_b32_dpp v4, v3 quad_perm:[1,0,3,2] row_mask:0xf bank_mask:0xf
	s_and_saveexec_b64 s[2:3], s[0:1]
	s_cbranch_execz .LBB0_1030
	s_waitcnt lgkmcnt(0)
	v_cvt_pk_bf16_f32 v3, v3, v4
	v_add_co_u32_e32 v4, vcc, 0x108000, v82
	s_nop 1
	v_addc_co_u32_e32 v5, vcc, 0, v83, vcc
	global_store_dword v[4:5], v3, off
.LBB0_1030:
	s_or_b64 exec, exec, s[2:3]
	v_mul_f32_e32 v3, v25, v2
	s_waitcnt lgkmcnt(0)
	s_nop 1
	v_mov_b32_dpp v4, v3 quad_perm:[1,0,3,2] row_mask:0xf bank_mask:0xf
	s_and_saveexec_b64 s[2:3], s[0:1]
	s_cbranch_execz .LBB0_1032
	s_waitcnt lgkmcnt(0)
	v_cvt_pk_bf16_f32 v3, v3, v4
	v_add_co_u32_e32 v4, vcc, 0x108000, v82
	s_nop 1
	v_addc_co_u32_e32 v5, vcc, 0, v83, vcc
	global_store_dword v[4:5], v3, off offset:64
.LBB0_1032:
	s_or_b64 exec, exec, s[2:3]
	v_mul_f32_e32 v3, v41, v2
	s_waitcnt lgkmcnt(0)
	s_nop 1
	v_mov_b32_dpp v4, v3 quad_perm:[1,0,3,2] row_mask:0xf bank_mask:0xf
	s_and_saveexec_b64 s[2:3], s[0:1]
	s_cbranch_execz .LBB0_1034
	s_waitcnt lgkmcnt(0)
	v_cvt_pk_bf16_f32 v3, v3, v4
	v_add_co_u32_e32 v4, vcc, 0x108000, v82
	s_nop 1
	v_addc_co_u32_e32 v5, vcc, 0, v83, vcc
	global_store_dword v[4:5], v3, off offset:128
.LBB0_1034:
	s_or_b64 exec, exec, s[2:3]
	v_mul_f32_e32 v2, v57, v2
	s_nop 1
	v_mov_b32_dpp v3, v2 quad_perm:[1,0,3,2] row_mask:0xf bank_mask:0xf
	s_and_saveexec_b64 s[2:3], s[0:1]
	s_cbranch_execz .LBB0_1036
	s_waitcnt lgkmcnt(0)
	v_cvt_pk_bf16_f32 v4, v2, v3
	v_add_co_u32_e32 v2, vcc, 0x108000, v82
	s_nop 1
	v_addc_co_u32_e32 v3, vcc, 0, v83, vcc
	global_store_dword v[2:3], v4, off offset:192
.LBB0_1036:
	s_or_b64 exec, exec, s[2:3]
	v_rcp_f32_e32 v2, v70
	s_waitcnt lgkmcnt(0)
	v_mul_f32_e32 v3, v10, v2
	s_nop 1
	v_mov_b32_dpp v4, v3 quad_perm:[1,0,3,2] row_mask:0xf bank_mask:0xf
	s_and_saveexec_b64 s[2:3], s[0:1]
	s_cbranch_execz .LBB0_1038
	s_waitcnt lgkmcnt(0)
	v_cvt_pk_bf16_f32 v3, v3, v4
	v_add_co_u32_e32 v4, vcc, 0x180000, v82
	s_nop 1
	v_addc_co_u32_e32 v5, vcc, 0, v83, vcc
	global_store_dword v[4:5], v3, off
.LBB0_1038:
	s_or_b64 exec, exec, s[2:3]
	v_mul_f32_e32 v3, v26, v2
	s_waitcnt lgkmcnt(0)
	s_nop 1
	v_mov_b32_dpp v4, v3 quad_perm:[1,0,3,2] row_mask:0xf bank_mask:0xf
	s_and_saveexec_b64 s[2:3], s[0:1]
	s_cbranch_execz .LBB0_1040
	s_waitcnt lgkmcnt(0)
	v_cvt_pk_bf16_f32 v3, v3, v4
	v_add_co_u32_e32 v4, vcc, 0x180000, v82
	s_nop 1
	v_addc_co_u32_e32 v5, vcc, 0, v83, vcc
	global_store_dword v[4:5], v3, off offset:64
.LBB0_1040:
	s_or_b64 exec, exec, s[2:3]
	v_mul_f32_e32 v3, v42, v2
	s_waitcnt lgkmcnt(0)
	s_nop 1
	v_mov_b32_dpp v4, v3 quad_perm:[1,0,3,2] row_mask:0xf bank_mask:0xf
	s_and_saveexec_b64 s[2:3], s[0:1]
	s_cbranch_execz .LBB0_1042
	s_waitcnt lgkmcnt(0)
	v_cvt_pk_bf16_f32 v3, v3, v4
	v_add_co_u32_e32 v4, vcc, 0x180000, v82
	s_nop 1
	v_addc_co_u32_e32 v5, vcc, 0, v83, vcc
	global_store_dword v[4:5], v3, off offset:128
.LBB0_1042:
	s_or_b64 exec, exec, s[2:3]
	v_mul_f32_e32 v2, v58, v2
	s_nop 1
	v_mov_b32_dpp v3, v2 quad_perm:[1,0,3,2] row_mask:0xf bank_mask:0xf
	s_and_saveexec_b64 s[2:3], s[0:1]
	s_cbranch_execz .LBB0_1044
	s_waitcnt lgkmcnt(0)
	v_cvt_pk_bf16_f32 v4, v2, v3
	v_add_co_u32_e32 v2, vcc, 0x180000, v82
	s_nop 1
	v_addc_co_u32_e32 v3, vcc, 0, v83, vcc
	global_store_dword v[2:3], v4, off offset:192
.LBB0_1044:
	s_or_b64 exec, exec, s[2:3]
	v_rcp_f32_e32 v2, v71
	s_waitcnt lgkmcnt(0)
	v_mul_f32_e32 v3, v11, v2
	s_nop 1
	v_mov_b32_dpp v4, v3 quad_perm:[1,0,3,2] row_mask:0xf bank_mask:0xf
	s_and_saveexec_b64 s[2:3], s[0:1]
	s_cbranch_execz .LBB0_1046
	s_waitcnt lgkmcnt(0)
	v_cvt_pk_bf16_f32 v3, v3, v4
	v_add_co_u32_e32 v4, vcc, 0x198000, v82
	s_nop 1
	v_addc_co_u32_e32 v5, vcc, 0, v83, vcc
	global_store_dword v[4:5], v3, off
.LBB0_1046:
	s_or_b64 exec, exec, s[2:3]
	v_mul_f32_e32 v3, v27, v2
	s_waitcnt lgkmcnt(0)
	s_nop 1
	v_mov_b32_dpp v4, v3 quad_perm:[1,0,3,2] row_mask:0xf bank_mask:0xf
	s_and_saveexec_b64 s[2:3], s[0:1]
	s_cbranch_execz .LBB0_1048
	s_waitcnt lgkmcnt(0)
	v_cvt_pk_bf16_f32 v3, v3, v4
	v_add_co_u32_e32 v4, vcc, 0x198000, v82
	s_nop 1
	v_addc_co_u32_e32 v5, vcc, 0, v83, vcc
	global_store_dword v[4:5], v3, off offset:64
.LBB0_1048:
	s_or_b64 exec, exec, s[2:3]
	v_mul_f32_e32 v3, v43, v2
	s_waitcnt lgkmcnt(0)
	s_nop 1
	v_mov_b32_dpp v4, v3 quad_perm:[1,0,3,2] row_mask:0xf bank_mask:0xf
	s_and_saveexec_b64 s[2:3], s[0:1]
	s_cbranch_execz .LBB0_1050
	s_waitcnt lgkmcnt(0)
	v_cvt_pk_bf16_f32 v3, v3, v4
	v_add_co_u32_e32 v4, vcc, 0x198000, v82
	s_nop 1
	v_addc_co_u32_e32 v5, vcc, 0, v83, vcc
	global_store_dword v[4:5], v3, off offset:128
.LBB0_1050:
	s_or_b64 exec, exec, s[2:3]
	v_mul_f32_e32 v2, v59, v2
	s_nop 1
	v_mov_b32_dpp v3, v2 quad_perm:[1,0,3,2] row_mask:0xf bank_mask:0xf
	s_and_saveexec_b64 s[2:3], s[0:1]
	s_cbranch_execz .LBB0_1052
	s_waitcnt lgkmcnt(0)
	v_cvt_pk_bf16_f32 v4, v2, v3
	v_add_co_u32_e32 v2, vcc, 0x198000, v82
	s_nop 1
	v_addc_co_u32_e32 v3, vcc, 0, v83, vcc
	global_store_dword v[2:3], v4, off offset:192
.LBB0_1052:
	s_or_b64 exec, exec, s[2:3]
	v_rcp_f32_e32 v2, v72
	s_waitcnt lgkmcnt(0)
	v_mul_f32_e32 v3, v12, v2
	s_nop 1
	v_mov_b32_dpp v4, v3 quad_perm:[1,0,3,2] row_mask:0xf bank_mask:0xf
	s_and_saveexec_b64 s[2:3], s[0:1]
	s_cbranch_execz .LBB0_1054
	s_waitcnt lgkmcnt(0)
	v_cvt_pk_bf16_f32 v3, v3, v4
	v_add_co_u32_e32 v4, vcc, 0x1b0000, v82
	s_nop 1
	v_addc_co_u32_e32 v5, vcc, 0, v83, vcc
	global_store_dword v[4:5], v3, off
.LBB0_1054:
	s_or_b64 exec, exec, s[2:3]
	v_mul_f32_e32 v3, v28, v2
	s_waitcnt lgkmcnt(0)
	s_nop 1
	v_mov_b32_dpp v4, v3 quad_perm:[1,0,3,2] row_mask:0xf bank_mask:0xf
	s_and_saveexec_b64 s[2:3], s[0:1]
	s_cbranch_execz .LBB0_1056
	s_waitcnt lgkmcnt(0)
	v_cvt_pk_bf16_f32 v3, v3, v4
	v_add_co_u32_e32 v4, vcc, 0x1b0000, v82
	s_nop 1
	v_addc_co_u32_e32 v5, vcc, 0, v83, vcc
	global_store_dword v[4:5], v3, off offset:64
.LBB0_1056:
	s_or_b64 exec, exec, s[2:3]
	v_mul_f32_e32 v3, v44, v2
	s_waitcnt lgkmcnt(0)
	s_nop 1
	v_mov_b32_dpp v4, v3 quad_perm:[1,0,3,2] row_mask:0xf bank_mask:0xf
	s_and_saveexec_b64 s[2:3], s[0:1]
	s_cbranch_execz .LBB0_1058
	s_waitcnt lgkmcnt(0)
	v_cvt_pk_bf16_f32 v3, v3, v4
	v_add_co_u32_e32 v4, vcc, 0x1b0000, v82
	s_nop 1
	v_addc_co_u32_e32 v5, vcc, 0, v83, vcc
	global_store_dword v[4:5], v3, off offset:128
.LBB0_1058:
	s_or_b64 exec, exec, s[2:3]
	v_mul_f32_e32 v2, v60, v2
	s_nop 1
	v_mov_b32_dpp v3, v2 quad_perm:[1,0,3,2] row_mask:0xf bank_mask:0xf
	s_and_saveexec_b64 s[2:3], s[0:1]
	s_cbranch_execz .LBB0_1060
	s_waitcnt lgkmcnt(0)
	v_cvt_pk_bf16_f32 v4, v2, v3
	v_add_co_u32_e32 v2, vcc, 0x1b0000, v82
	s_nop 1
	v_addc_co_u32_e32 v3, vcc, 0, v83, vcc
	global_store_dword v[2:3], v4, off offset:192
.LBB0_1060:
	s_or_b64 exec, exec, s[2:3]
	v_rcp_f32_e32 v2, v73
	s_waitcnt lgkmcnt(0)
	v_mul_f32_e32 v3, v13, v2
	s_nop 1
	v_mov_b32_dpp v4, v3 quad_perm:[1,0,3,2] row_mask:0xf bank_mask:0xf
	s_and_saveexec_b64 s[2:3], s[0:1]
	s_cbranch_execz .LBB0_1062
	s_waitcnt lgkmcnt(0)
	v_cvt_pk_bf16_f32 v3, v3, v4
	v_add_co_u32_e32 v4, vcc, 0x1c8000, v82
	s_nop 1
	v_addc_co_u32_e32 v5, vcc, 0, v83, vcc
	global_store_dword v[4:5], v3, off
.LBB0_1062:
	s_or_b64 exec, exec, s[2:3]
	v_mul_f32_e32 v3, v29, v2
	s_waitcnt lgkmcnt(0)
	s_nop 1
	v_mov_b32_dpp v4, v3 quad_perm:[1,0,3,2] row_mask:0xf bank_mask:0xf
	s_and_saveexec_b64 s[2:3], s[0:1]
	s_cbranch_execz .LBB0_1064
	s_waitcnt lgkmcnt(0)
	v_cvt_pk_bf16_f32 v3, v3, v4
	v_add_co_u32_e32 v4, vcc, 0x1c8000, v82
	s_nop 1
	v_addc_co_u32_e32 v5, vcc, 0, v83, vcc
	global_store_dword v[4:5], v3, off offset:64
.LBB0_1064:
	s_or_b64 exec, exec, s[2:3]
	v_mul_f32_e32 v3, v45, v2
	s_waitcnt lgkmcnt(0)
	s_nop 1
	v_mov_b32_dpp v4, v3 quad_perm:[1,0,3,2] row_mask:0xf bank_mask:0xf
	s_and_saveexec_b64 s[2:3], s[0:1]
	s_cbranch_execz .LBB0_1066
	s_waitcnt lgkmcnt(0)
	v_cvt_pk_bf16_f32 v3, v3, v4
	v_add_co_u32_e32 v4, vcc, 0x1c8000, v82
	s_nop 1
	v_addc_co_u32_e32 v5, vcc, 0, v83, vcc
	global_store_dword v[4:5], v3, off offset:128
.LBB0_1066:
	s_or_b64 exec, exec, s[2:3]
	v_mul_f32_e32 v2, v61, v2
	s_nop 1
	v_mov_b32_dpp v3, v2 quad_perm:[1,0,3,2] row_mask:0xf bank_mask:0xf
	s_and_saveexec_b64 s[2:3], s[0:1]
	s_cbranch_execz .LBB0_1068
	s_waitcnt lgkmcnt(0)
	v_cvt_pk_bf16_f32 v4, v2, v3
	v_add_co_u32_e32 v2, vcc, 0x1c8000, v82
	s_nop 1
	v_addc_co_u32_e32 v3, vcc, 0, v83, vcc
	global_store_dword v[2:3], v4, off offset:192
.LBB0_1068:
	s_or_b64 exec, exec, s[2:3]
	v_rcp_f32_e32 v2, v66
	s_waitcnt lgkmcnt(0)
	v_mul_f32_e32 v3, v14, v2
	s_nop 1
	v_mov_b32_dpp v4, v3 quad_perm:[1,0,3,2] row_mask:0xf bank_mask:0xf
	s_and_saveexec_b64 s[2:3], s[0:1]
	s_cbranch_execz .LBB0_1070
	s_waitcnt lgkmcnt(0)
	v_cvt_pk_bf16_f32 v3, v3, v4
	v_add_co_u32_e32 v4, vcc, 0x240000, v82
	s_nop 1
	v_addc_co_u32_e32 v5, vcc, 0, v83, vcc
	global_store_dword v[4:5], v3, off
.LBB0_1070:
	s_or_b64 exec, exec, s[2:3]
	v_mul_f32_e32 v3, v30, v2
	s_waitcnt lgkmcnt(0)
	s_nop 1
	v_mov_b32_dpp v4, v3 quad_perm:[1,0,3,2] row_mask:0xf bank_mask:0xf
	s_and_saveexec_b64 s[2:3], s[0:1]
	s_cbranch_execz .LBB0_1072
	s_waitcnt lgkmcnt(0)
	v_cvt_pk_bf16_f32 v3, v3, v4
	v_add_co_u32_e32 v4, vcc, 0x240000, v82
	s_nop 1
	v_addc_co_u32_e32 v5, vcc, 0, v83, vcc
	global_store_dword v[4:5], v3, off offset:64
.LBB0_1072:
	s_or_b64 exec, exec, s[2:3]
	v_mul_f32_e32 v3, v46, v2
	s_waitcnt lgkmcnt(0)
	s_nop 1
	v_mov_b32_dpp v4, v3 quad_perm:[1,0,3,2] row_mask:0xf bank_mask:0xf
	s_and_saveexec_b64 s[2:3], s[0:1]
	s_cbranch_execz .LBB0_1074
	s_waitcnt lgkmcnt(0)
	v_cvt_pk_bf16_f32 v3, v3, v4
	v_add_co_u32_e32 v4, vcc, 0x240000, v82
	s_nop 1
	v_addc_co_u32_e32 v5, vcc, 0, v83, vcc
	global_store_dword v[4:5], v3, off offset:128
.LBB0_1074:
	s_or_b64 exec, exec, s[2:3]
	v_mul_f32_e32 v2, v62, v2
	s_nop 1
	v_mov_b32_dpp v3, v2 quad_perm:[1,0,3,2] row_mask:0xf bank_mask:0xf
	s_and_saveexec_b64 s[2:3], s[0:1]
	s_cbranch_execz .LBB0_1076
	s_waitcnt lgkmcnt(0)
	v_cvt_pk_bf16_f32 v4, v2, v3
	v_add_co_u32_e32 v2, vcc, 0x240000, v82
	s_nop 1
	v_addc_co_u32_e32 v3, vcc, 0, v83, vcc
	global_store_dword v[2:3], v4, off offset:192
.LBB0_1076:
	s_or_b64 exec, exec, s[2:3]
	v_rcp_f32_e32 v2, v67
	s_waitcnt lgkmcnt(0)
	v_mul_f32_e32 v3, v15, v2
	s_nop 1
	v_mov_b32_dpp v4, v3 quad_perm:[1,0,3,2] row_mask:0xf bank_mask:0xf
	s_and_saveexec_b64 s[2:3], s[0:1]
	s_cbranch_execz .LBB0_1078
	s_waitcnt lgkmcnt(0)
	v_cvt_pk_bf16_f32 v3, v3, v4
	v_add_co_u32_e32 v4, vcc, 0x258000, v82
	s_nop 1
	v_addc_co_u32_e32 v5, vcc, 0, v83, vcc
	global_store_dword v[4:5], v3, off
.LBB0_1078:
	s_or_b64 exec, exec, s[2:3]
	v_mul_f32_e32 v3, v31, v2
	s_waitcnt lgkmcnt(0)
	s_nop 1
	v_mov_b32_dpp v4, v3 quad_perm:[1,0,3,2] row_mask:0xf bank_mask:0xf
	s_and_saveexec_b64 s[2:3], s[0:1]
	s_cbranch_execz .LBB0_1080
	s_waitcnt lgkmcnt(0)
	v_cvt_pk_bf16_f32 v3, v3, v4
	v_add_co_u32_e32 v4, vcc, 0x258000, v82
	s_nop 1
	v_addc_co_u32_e32 v5, vcc, 0, v83, vcc
	global_store_dword v[4:5], v3, off offset:64
.LBB0_1080:
	s_or_b64 exec, exec, s[2:3]
	v_mul_f32_e32 v3, v47, v2
	s_waitcnt lgkmcnt(0)
	s_nop 1
	v_mov_b32_dpp v4, v3 quad_perm:[1,0,3,2] row_mask:0xf bank_mask:0xf
	s_and_saveexec_b64 s[2:3], s[0:1]
	s_cbranch_execz .LBB0_1082
	s_waitcnt lgkmcnt(0)
	v_cvt_pk_bf16_f32 v3, v3, v4
	v_add_co_u32_e32 v4, vcc, 0x258000, v82
	s_nop 1
	v_addc_co_u32_e32 v5, vcc, 0, v83, vcc
	global_store_dword v[4:5], v3, off offset:128
.LBB0_1082:
	s_or_b64 exec, exec, s[2:3]
	v_mul_f32_e32 v2, v63, v2
	s_nop 1
	v_mov_b32_dpp v3, v2 quad_perm:[1,0,3,2] row_mask:0xf bank_mask:0xf
	s_and_saveexec_b64 s[2:3], s[0:1]
	s_cbranch_execz .LBB0_1084
	s_waitcnt lgkmcnt(0)
	v_cvt_pk_bf16_f32 v4, v2, v3
	v_add_co_u32_e32 v2, vcc, 0x258000, v82
	s_nop 1
	v_addc_co_u32_e32 v3, vcc, 0, v83, vcc
	global_store_dword v[2:3], v4, off offset:192
.LBB0_1084:
	s_or_b64 exec, exec, s[2:3]
	v_rcp_f32_e32 v2, v68
	s_waitcnt lgkmcnt(0)
	v_mul_f32_e32 v3, v16, v2
	s_nop 1
	v_mov_b32_dpp v4, v3 quad_perm:[1,0,3,2] row_mask:0xf bank_mask:0xf
	s_and_saveexec_b64 s[2:3], s[0:1]
	s_cbranch_execz .LBB0_1086
	s_waitcnt lgkmcnt(0)
	v_cvt_pk_bf16_f32 v3, v3, v4
	v_add_co_u32_e32 v4, vcc, 0x270000, v82
	s_nop 1
	v_addc_co_u32_e32 v5, vcc, 0, v83, vcc
	global_store_dword v[4:5], v3, off
.LBB0_1086:
	s_or_b64 exec, exec, s[2:3]
	v_mul_f32_e32 v3, v32, v2
	s_waitcnt lgkmcnt(0)
	s_nop 1
	v_mov_b32_dpp v4, v3 quad_perm:[1,0,3,2] row_mask:0xf bank_mask:0xf
	s_and_saveexec_b64 s[2:3], s[0:1]
	s_cbranch_execz .LBB0_1088
	s_waitcnt lgkmcnt(0)
	v_cvt_pk_bf16_f32 v3, v3, v4
	v_add_co_u32_e32 v4, vcc, 0x270000, v82
	s_nop 1
	v_addc_co_u32_e32 v5, vcc, 0, v83, vcc
	global_store_dword v[4:5], v3, off offset:64
.LBB0_1088:
	s_or_b64 exec, exec, s[2:3]
	v_mul_f32_e32 v3, v48, v2
	s_waitcnt lgkmcnt(0)
	s_nop 1
	v_mov_b32_dpp v4, v3 quad_perm:[1,0,3,2] row_mask:0xf bank_mask:0xf
	s_and_saveexec_b64 s[2:3], s[0:1]
	s_cbranch_execz .LBB0_1090
	s_waitcnt lgkmcnt(0)
	v_cvt_pk_bf16_f32 v3, v3, v4
	v_add_co_u32_e32 v4, vcc, 0x270000, v82
	s_nop 1
	v_addc_co_u32_e32 v5, vcc, 0, v83, vcc
	global_store_dword v[4:5], v3, off offset:128
.LBB0_1090:
	s_or_b64 exec, exec, s[2:3]
	v_mul_f32_e32 v2, v64, v2
	s_nop 1
	v_mov_b32_dpp v3, v2 quad_perm:[1,0,3,2] row_mask:0xf bank_mask:0xf
	s_and_saveexec_b64 s[2:3], s[0:1]
	s_cbranch_execz .LBB0_1092
	s_waitcnt lgkmcnt(0)
	v_cvt_pk_bf16_f32 v4, v2, v3
	v_add_co_u32_e32 v2, vcc, 0x270000, v82
	s_nop 1
	v_addc_co_u32_e32 v3, vcc, 0, v83, vcc
	global_store_dword v[2:3], v4, off offset:192
.LBB0_1092:
	s_or_b64 exec, exec, s[2:3]
	v_rcp_f32_e32 v2, v69
	s_waitcnt lgkmcnt(0)
	v_mul_f32_e32 v3, v17, v2
	s_nop 1
	v_mov_b32_dpp v4, v3 quad_perm:[1,0,3,2] row_mask:0xf bank_mask:0xf
	s_and_saveexec_b64 s[2:3], s[0:1]
	s_cbranch_execz .LBB0_1094
	s_waitcnt lgkmcnt(0)
	v_cvt_pk_bf16_f32 v3, v3, v4
	v_add_co_u32_e32 v4, vcc, 0x288000, v82
	s_nop 1
	v_addc_co_u32_e32 v5, vcc, 0, v83, vcc
	global_store_dword v[4:5], v3, off
.LBB0_1094:
	s_or_b64 exec, exec, s[2:3]
	v_mul_f32_e32 v3, v33, v2
	s_waitcnt lgkmcnt(0)
	s_nop 1
	v_mov_b32_dpp v4, v3 quad_perm:[1,0,3,2] row_mask:0xf bank_mask:0xf
	s_and_saveexec_b64 s[2:3], s[0:1]
	s_cbranch_execz .LBB0_1096
	s_waitcnt lgkmcnt(0)
	v_cvt_pk_bf16_f32 v3, v3, v4
	v_add_co_u32_e32 v4, vcc, 0x288000, v82
	s_nop 1
	v_addc_co_u32_e32 v5, vcc, 0, v83, vcc
	global_store_dword v[4:5], v3, off offset:64
.LBB0_1096:
	s_or_b64 exec, exec, s[2:3]
	v_mul_f32_e32 v3, v49, v2
	s_waitcnt lgkmcnt(0)
	s_nop 1
	v_mov_b32_dpp v4, v3 quad_perm:[1,0,3,2] row_mask:0xf bank_mask:0xf
	s_and_saveexec_b64 s[2:3], s[0:1]
	s_cbranch_execz .LBB0_1098
	s_waitcnt lgkmcnt(0)
	v_cvt_pk_bf16_f32 v3, v3, v4
	v_add_co_u32_e32 v4, vcc, 0x288000, v82
	s_nop 1
	v_addc_co_u32_e32 v5, vcc, 0, v83, vcc
	global_store_dword v[4:5], v3, off offset:128
.LBB0_1098:
	s_or_b64 exec, exec, s[2:3]
	v_mul_f32_e32 v2, v65, v2
	s_nop 1
	v_mov_b32_dpp v3, v2 quad_perm:[1,0,3,2] row_mask:0xf bank_mask:0xf
	s_and_saveexec_b64 s[2:3], s[0:1]
	s_cbranch_execz .LBB0_613
	s_waitcnt lgkmcnt(0)
	v_cvt_pk_bf16_f32 v4, v2, v3
	v_add_co_u32_e32 v2, vcc, 0x288000, v82
	s_nop 1
	v_addc_co_u32_e32 v3, vcc, 0, v83, vcc
	global_store_dword v[2:3], v4, off offset:192
	s_branch .LBB0_613
